# GEMM loops: first K-iteration peeled with SrcC=0 on each accumulator's first MFMA; the 128 v_mov zero-inits per tile removed
# speedup vs baseline: 1.0091x; 1.0018x over previous
; #define PG8_WAIT_V(n) asm volatile("s_waitcnt vmcnt(" #n ")" ::: "memory")
; #define PG8_WAIT_L(n) asm volatile("s_waitcnt lgkmcnt(" #n ")" ::: "memory")
; template <class Epi, class Sched, bool ALIGN_EPI = false, bool SP2 = false>
; __device__ __forceinline__ void gemm_phase(PG8_LAS unsigned char* lds, const Gemm g, const Sched& S, const Epi& E) {
;     ...
;         const bool has_next = S.next(ui + 1, nxt);
;         const char* nA = has_next ? (const char*)g.A + (size_t)nxt.pm * tstep + (size_t)nxt.pn * g.a_gs : cA; const char* nB = has_next ? (const char*)g.Bt + (size_t)nxt.pn * tstep : cB;
;         for (int t = 0; t < nt; t += 2) {
;             const bool last = (t == nt - 2);
;             const char* a1 = cA + (size_t)(t + 1) * kstep;
;             const char* a2 = last ? nA : cA + (size_t)(t + 2) * kstep; const char* b2 = last ? nB : cB + (size_t)(t + 2) * kstep;
;             const char* a3 = a2 + kstep; const char* b3 = b2 + kstep;
;             if (last && has_next) S.a_ready(nxt);
;             if constexpr (SP2) {
;             PG8_LDB(B0, 0, 0); PG8_LDB(B1, 0, 1); PG8_SCHED; PG8_LDA(At, 0, 0); PG8_STAGE(PG8_SA(1, 1), a1 + hstep, voffA);
;             PG8_WAIT_V(8); PG8_WAIT_L(0); PG8_BAR; PG8_MMA(0, 0, At, B0); PG8_MMA(0, 1, At, B1); PG8_BAR; PG8_SCHED;
;             PG8_LDA(At, 0, 1); PG8_STAGE(PG8_SB(0, 0), b2, voffB); PG8_STAGE(PG8_SB(0, 1), b2 + hstep, voffB); PG8_STAGE(PG8_SA(0, 0), a2, voffA);
;             PG8_WAIT_V(8); PG8_WAIT_L(0); PG8_BAR; PG8_MMA(1, 0, At, B0); PG8_MMA(1, 1, At, B1); PG8_BAR; PG8_SCHED;
;             PG8_LDB(B0, 1, 0); PG8_LDB(B1, 1, 1); PG8_SCHED; PG8_LDA(At, 1, 0); PG8_STAGE(PG8_SA(0, 1), a2 + hstep, voffA);
;             PG8_WAIT_V(8); PG8_WAIT_L(0); PG8_BAR; PG8_MMA(0, 0, At, B0); PG8_MMA(0, 1, At, B1); PG8_BAR; PG8_SCHED;
;             PG8_LDA(At, 1, 1); PG8_STAGE(PG8_SB(1, 0), b3, voffB); PG8_STAGE(PG8_SB(1, 1), b3 + hstep, voffB); PG8_STAGE(PG8_SA(1, 0), a3, voffA);
;             PG8_WAIT_V(8); PG8_WAIT_L(0); PG8_BAR; PG8_MMA(1, 0, At, B0); PG8_MMA(1, 1, At, B1); PG8_BAR; PG8_SCHED;
;     ...
; #pragma unroll
;         for (int a = 0; a < 2; ++a)
; #pragma unroll
;             for (int b = 0; b < 2; ++b)
; #pragma unroll
;                 for (int m = 0; m < 4; ++m)
; #pragma unroll
;                     for (int n = 0; n < 2; ++n) acc[a][b][m][n] = (f32x4){0.f, 0.f, 0.f, 0.f};
.LBB0_218:
	s_ashr_i32 s73, s72, 31
	s_lshl_b64 s[38:39], s[72:73], 19
	s_add_u32 s74, s10, s38
	s_addc_u32 s75, s11, s39
	s_and_b64 s[38:39], s[44:45], exec
	s_cselect_b32 s50, s75, s49
	s_cselect_b32 s51, s74, s48
	s_ashr_i32 s71, s70, 31
	s_lshl_b64 s[38:39], s[70:71], 19
	s_add_u32 s76, s62, s38
	s_addc_u32 s77, s63, s39
	s_and_b64 s[38:39], s[44:45], exec
	s_cselect_b32 s52, s77, s47
	s_cselect_b32 s53, s76, s46
	s_add_u32 s38, s48, 0x40080
	s_addc_u32 s39, s49, 0
	s_add_u32 s71, s46, 0x100
	s_addc_u32 s73, s47, 0
	s_mov_b32 vcc_lo, -2
	s_add_u32 s46, s38, 0xfffc0080
	s_addc_u32 s47, s39, -1
	s_add_i32 s56, 0, 0x10000
	s_cmp_eq_u32 vcc_lo, 12
	s_cselect_b32 s49, s50, s47
	s_cselect_b32 s48, s51, s46
	s_cselect_b32 s47, s52, s73
	s_cselect_b32 s46, s53, s71
	s_add_i32 vcc_hi, 0, 0x14000
	v_add_u32_e32 v152, s56, v165
	v_add_u32_e32 v169, vcc_hi, v165
	ds_read_b128 v[128:131], v152
	ds_read_b128 v[144:147], v152 offset:1024
	ds_read_b128 v[148:151], v152 offset:2048
	ds_read_b128 v[152:155], v152 offset:3072
	ds_read_b128 v[156:159], v169
	ds_read_b128 v[160:163], v169 offset:1024
	ds_read_b128 v[170:173], v169 offset:2048
	ds_read_b128 v[180:183], v169 offset:3072
	v_lshl_add_u64 v[176:177], s[38:39], 0, v[140:141]
	s_add_i32 m0, s9, 0xc000
	ds_read_b128 v[184:187], v168
	ds_read_b128 v[188:191], v168 offset:1024
	ds_read_b128 v[192:195], v168 offset:2048
	ds_read_b128 v[196:199], v168 offset:3072
	ds_read_b128 v[200:203], v168 offset:4096
	ds_read_b128 v[204:207], v168 offset:5120
	ds_read_b128 v[218:221], v168 offset:6144
	ds_read_b128 v[222:225], v168 offset:7168
	global_load_lds_dwordx4 v[176:177], off
	v_lshl_add_u64 v[176:177], s[38:39], 0, v[142:143]
	s_add_i32 m0, s9, 0xe000
	s_nop 0
	global_load_lds_dwordx4 v[176:177], off
	s_waitcnt vmcnt(8)
	s_waitcnt lgkmcnt(0)
	s_barrier
	s_setprio 1
	s_waitcnt lgkmcnt(0)
	v_mfma_f32_16x16x32_bf16 v[124:127], v[128:131], v[184:187], 0
	v_mfma_f32_16x16x32_bf16 v[120:123], v[148:151], v[184:187], 0
	v_mfma_f32_16x16x32_bf16 v[108:111], v[128:131], v[192:195], 0
	v_mfma_f32_16x16x32_bf16 v[104:107], v[148:151], v[192:195], 0
	v_mfma_f32_16x16x32_bf16 v[92:95], v[128:131], v[200:203], 0
	v_mfma_f32_16x16x32_bf16 v[88:91], v[148:151], v[200:203], 0
	v_mfma_f32_16x16x32_bf16 v[76:79], v[128:131], v[218:221], 0
	v_mfma_f32_16x16x32_bf16 v[72:75], v[148:151], v[218:221], 0
	v_mfma_f32_16x16x32_bf16 v[124:127], v[144:147], v[188:191], v[124:127]
	v_mfma_f32_16x16x32_bf16 v[120:123], v[152:155], v[188:191], v[120:123]
	v_mfma_f32_16x16x32_bf16 v[108:111], v[144:147], v[196:199], v[108:111]
	v_mfma_f32_16x16x32_bf16 v[104:107], v[152:155], v[196:199], v[104:107]
	v_mfma_f32_16x16x32_bf16 v[92:95], v[144:147], v[204:207], v[92:95]
	v_mfma_f32_16x16x32_bf16 v[88:91], v[152:155], v[204:207], v[88:91]
	v_mfma_f32_16x16x32_bf16 v[76:79], v[144:147], v[222:225], v[76:79]
	v_mfma_f32_16x16x32_bf16 v[72:75], v[152:155], v[222:225], v[72:75]
	v_mfma_f32_16x16x32_bf16 v[116:119], v[156:159], v[184:187], 0
	v_mfma_f32_16x16x32_bf16 v[112:115], v[170:173], v[184:187], 0
	v_mfma_f32_16x16x32_bf16 v[100:103], v[156:159], v[192:195], 0
	v_mfma_f32_16x16x32_bf16 v[96:99], v[170:173], v[192:195], 0
	v_mfma_f32_16x16x32_bf16 v[84:87], v[156:159], v[200:203], 0
	v_mfma_f32_16x16x32_bf16 v[80:83], v[170:173], v[200:203], 0
	v_mfma_f32_16x16x32_bf16 v[68:71], v[156:159], v[218:221], 0
	v_mfma_f32_16x16x32_bf16 v[64:67], v[170:173], v[218:221], 0
	v_mfma_f32_16x16x32_bf16 v[116:119], v[160:163], v[188:191], v[116:119]
	v_mfma_f32_16x16x32_bf16 v[112:115], v[180:183], v[188:191], v[112:115]
	v_mfma_f32_16x16x32_bf16 v[100:103], v[160:163], v[196:199], v[100:103]
	v_mfma_f32_16x16x32_bf16 v[96:99], v[180:183], v[196:199], v[96:99]
	v_mfma_f32_16x16x32_bf16 v[84:87], v[160:163], v[204:207], v[84:87]
	v_mfma_f32_16x16x32_bf16 v[80:83], v[180:183], v[204:207], v[80:83]
	v_mfma_f32_16x16x32_bf16 v[68:71], v[160:163], v[222:225], v[68:71]
	v_mfma_f32_16x16x32_bf16 v[64:67], v[180:183], v[222:225], v[64:67]
	s_setprio 0
	s_barrier
	s_add_i32 s56, s56, s8
	v_lshl_add_u64 v[176:177], s[46:47], 0, v[174:175]
	s_mov_b32 m0, s56
	ds_read_b128 v[184:187], v168 offset:16384
	ds_read_b128 v[188:191], v168 offset:17408
	ds_read_b128 v[192:195], v168 offset:18432
	ds_read_b128 v[196:199], v168 offset:19456
	ds_read_b128 v[200:203], v168 offset:20480
	ds_read_b128 v[204:207], v168 offset:21504
	ds_read_b128 v[218:221], v168 offset:22528
	ds_read_b128 v[222:225], v168 offset:23552
	global_load_lds_dwordx4 v[176:177], off
	s_add_i32 m0, s56, 0x2000
	s_add_u32 s56, s46, 0x40000
	v_lshl_add_u64 v[178:179], s[46:47], 0, v[136:137]
	s_addc_u32 s57, s47, 0
	s_add_i32 vcc_hi, vcc_hi, s8
	global_load_lds_dwordx4 v[178:179], off
	v_lshl_add_u64 v[208:209], s[56:57], 0, v[174:175]
	s_mov_b32 m0, vcc_hi
	v_lshl_add_u64 v[226:227], s[48:49], 0, v[134:135]
	global_load_lds_dwordx4 v[208:209], off
	v_lshl_add_u64 v[208:209], s[56:57], 0, v[136:137]
	s_add_i32 m0, vcc_hi, 0x2000
	s_nop 0
	global_load_lds_dwordx4 v[208:209], off
	v_lshl_add_u64 v[208:209], s[48:49], 0, v[132:133]
	s_mov_b32 m0, s9
	s_nop 0
	global_load_lds_dwordx4 v[208:209], off
	s_mov_b32 m0, s79
	s_nop 0
	global_load_lds_dwordx4 v[226:227], off
	s_waitcnt vmcnt(8)
	s_waitcnt lgkmcnt(0)
	s_barrier
; #define PG8_STAGE(bufoff, gbase, voff) do { _Pragma("unroll") for (int _i = 0; _i < 2; ++_i) \
;         __builtin_amdgcn_global_load_lds((const unsigned*)((const char*)(gbase) + (voff)[_i]), (PG8_LAS unsigned*)(lds + (bufoff) + ldsw + _i * 8192), 16, 0, 0); } while (0)
; #define PG8_LDA(dst, b, h) do { _Pragma("unroll") for (int m = 0; m < 4; ++m) _Pragma("unroll") for (int k = 0; k < 2; ++k) dst[m][k] = *(const PG8_LAS bf16x8*)(lds + PG8_SA(b, h) + aoff + m * 2048 + k * 1024); } while (0)
; #define PG8_LDB(dst, b, h) do { _Pragma("unroll") for (int n = 0; n < 2; ++n) _Pragma("unroll") for (int k = 0; k < 2; ++k) dst[n][k] = *(const PG8_LAS bf16x8*)(lds + PG8_SB(b, h) + boff + n * 2048 + k * 1024); } while (0)
; #define PG8_MMA(ai, bj, At, Bt) do { __builtin_amdgcn_s_setprio(1); _Pragma("unroll") for (int m = 0; m < 4; ++m) _Pragma("unroll") for (int n = 0; n < 2; ++n) _Pragma("unroll") for (int k = 0; k < 2; ++k) \
;         acc[ai][bj][m][n] = __builtin_amdgcn_mfma_f32_16x16x32_bf16(Bt[n][k], At[m][k], acc[ai][bj][m][n], 0, 0, 0); __builtin_amdgcn_s_setprio(0); } while (0)
; #define PG8_WAIT_V(n) asm volatile("s_waitcnt vmcnt(" #n ")" ::: "memory")
; #define PG8_WAIT_L(n) asm volatile("s_waitcnt lgkmcnt(" #n ")" ::: "memory")
; #define PG8_BAR __builtin_amdgcn_s_barrier()
; #define PG8_SCHED __builtin_amdgcn_sched_barrier(0)
; template <class Epi, class Sched, bool ALIGN_EPI = false, bool SP2 = false>
; __device__ __forceinline__ void gemm_phase(PG8_LAS unsigned char* lds, const Gemm g, const Sched& S, const Epi& E) {
;     ...
;             PG8_WAIT_V(8); PG8_WAIT_L(0); PG8_BAR; PG8_MMA(1, 0, At, B0); PG8_MMA(1, 1, At, B1); PG8_BAR; PG8_SCHED;
;             PG8_LDB(B0, 1, 0); PG8_LDB(B1, 1, 1); PG8_SCHED; PG8_LDA(At, 1, 0); PG8_STAGE(PG8_SA(0, 1), a2 + hstep, voffA);
;             PG8_WAIT_V(8); PG8_WAIT_L(0); PG8_BAR; PG8_MMA(0, 0, At, B0); PG8_MMA(0, 1, At, B1); PG8_BAR; PG8_SCHED;
	s_setprio 1
	s_waitcnt lgkmcnt(0)
	v_mfma_f32_16x16x32_bf16 v[60:63], v[128:131], v[184:187], 0
	v_mfma_f32_16x16x32_bf16 v[56:59], v[148:151], v[184:187], 0
	v_mfma_f32_16x16x32_bf16 v[44:47], v[128:131], v[192:195], 0
	v_mfma_f32_16x16x32_bf16 v[40:43], v[148:151], v[192:195], 0
	v_mfma_f32_16x16x32_bf16 v[28:31], v[128:131], v[200:203], 0
	v_mfma_f32_16x16x32_bf16 v[24:27], v[148:151], v[200:203], 0
	v_mfma_f32_16x16x32_bf16 v[12:15], v[128:131], v[218:221], 0
	v_mfma_f32_16x16x32_bf16 v[8:11], v[148:151], v[218:221], 0
	v_mfma_f32_16x16x32_bf16 v[60:63], v[144:147], v[188:191], v[60:63]
	v_mfma_f32_16x16x32_bf16 v[56:59], v[152:155], v[188:191], v[56:59]
	v_mfma_f32_16x16x32_bf16 v[44:47], v[144:147], v[196:199], v[44:47]
	v_mfma_f32_16x16x32_bf16 v[40:43], v[152:155], v[196:199], v[40:43]
	v_mfma_f32_16x16x32_bf16 v[28:31], v[144:147], v[204:207], v[28:31]
	v_mfma_f32_16x16x32_bf16 v[24:27], v[152:155], v[204:207], v[24:27]
	v_mfma_f32_16x16x32_bf16 v[12:15], v[144:147], v[222:225], v[12:15]
	v_mfma_f32_16x16x32_bf16 v[8:11], v[152:155], v[222:225], v[8:11]
	v_mfma_f32_16x16x32_bf16 v[52:55], v[156:159], v[184:187], 0
	v_mfma_f32_16x16x32_bf16 v[48:51], v[170:173], v[184:187], 0
	v_mfma_f32_16x16x32_bf16 v[36:39], v[156:159], v[192:195], 0
	v_mfma_f32_16x16x32_bf16 v[32:35], v[170:173], v[192:195], 0
	v_mfma_f32_16x16x32_bf16 v[20:23], v[156:159], v[200:203], 0
	v_mfma_f32_16x16x32_bf16 v[16:19], v[170:173], v[200:203], 0
	v_mfma_f32_16x16x32_bf16 v[4:7], v[156:159], v[218:221], 0
	v_mfma_f32_16x16x32_bf16 v[0:3], v[170:173], v[218:221], 0
	v_mfma_f32_16x16x32_bf16 v[52:55], v[160:163], v[188:191], v[52:55]
	v_mfma_f32_16x16x32_bf16 v[48:51], v[180:183], v[188:191], v[48:51]
	v_mfma_f32_16x16x32_bf16 v[36:39], v[160:163], v[196:199], v[36:39]
	v_mfma_f32_16x16x32_bf16 v[32:35], v[180:183], v[196:199], v[32:35]
	v_mfma_f32_16x16x32_bf16 v[20:23], v[160:163], v[204:207], v[20:23]
	v_mfma_f32_16x16x32_bf16 v[16:19], v[180:183], v[204:207], v[16:19]
	v_mfma_f32_16x16x32_bf16 v[4:7], v[160:163], v[222:225], v[4:7]
	v_mfma_f32_16x16x32_bf16 v[0:3], v[180:183], v[222:225], v[0:3]
	s_setprio 0
	s_barrier
	s_add_i32 s56, 0, 0x18000
	s_add_i32 s57, 0, 0x1c000
	v_add_u32_e32 v152, s56, v165
	v_add_u32_e32 v169, s57, v165
	ds_read_b128 v[128:131], v152
	ds_read_b128 v[144:147], v152 offset:1024
	ds_read_b128 v[148:151], v152 offset:2048
	ds_read_b128 v[152:155], v152 offset:3072
	ds_read_b128 v[156:159], v169
	ds_read_b128 v[160:163], v169 offset:1024
	ds_read_b128 v[170:173], v169 offset:2048
	ds_read_b128 v[180:183], v169 offset:3072
	s_add_u32 s48, s48, 0x40000
	s_addc_u32 s49, s49, 0
	s_mov_b32 m0, s54
	v_lshl_add_u64 v[228:229], s[48:49], 0, v[132:133]
	ds_read_b128 v[184:187], v168 offset:32768
	ds_read_b128 v[188:191], v168 offset:33792
	ds_read_b128 v[192:195], v168 offset:34816
	ds_read_b128 v[196:199], v168 offset:35840
	ds_read_b128 v[200:203], v168 offset:36864
	ds_read_b128 v[204:207], v168 offset:37888
	ds_read_b128 v[218:221], v168 offset:38912
	ds_read_b128 v[222:225], v168 offset:39936
	global_load_lds_dwordx4 v[228:229], off
	v_lshl_add_u64 v[228:229], s[48:49], 0, v[134:135]
	s_mov_b32 m0, s55
	s_nop 0
	global_load_lds_dwordx4 v[228:229], off
	s_waitcnt vmcnt(8)
	s_waitcnt lgkmcnt(0)
	s_barrier
	s_setprio 1
	s_waitcnt lgkmcnt(0)
	v_mfma_f32_16x16x32_bf16 v[124:127], v[128:131], v[184:187], v[124:127]
	v_mfma_f32_16x16x32_bf16 v[120:123], v[148:151], v[184:187], v[120:123]
	v_mfma_f32_16x16x32_bf16 v[108:111], v[128:131], v[192:195], v[108:111]
	v_mfma_f32_16x16x32_bf16 v[104:107], v[148:151], v[192:195], v[104:107]
	v_mfma_f32_16x16x32_bf16 v[92:95], v[128:131], v[200:203], v[92:95]
	v_mfma_f32_16x16x32_bf16 v[88:91], v[148:151], v[200:203], v[88:91]
	v_mfma_f32_16x16x32_bf16 v[76:79], v[128:131], v[218:221], v[76:79]
	v_mfma_f32_16x16x32_bf16 v[72:75], v[148:151], v[218:221], v[72:75]
	v_mfma_f32_16x16x32_bf16 v[124:127], v[144:147], v[188:191], v[124:127]
	v_mfma_f32_16x16x32_bf16 v[120:123], v[152:155], v[188:191], v[120:123]
	v_mfma_f32_16x16x32_bf16 v[108:111], v[144:147], v[196:199], v[108:111]
	v_mfma_f32_16x16x32_bf16 v[104:107], v[152:155], v[196:199], v[104:107]
	v_mfma_f32_16x16x32_bf16 v[92:95], v[144:147], v[204:207], v[92:95]
	v_mfma_f32_16x16x32_bf16 v[88:91], v[152:155], v[204:207], v[88:91]
	v_mfma_f32_16x16x32_bf16 v[76:79], v[144:147], v[222:225], v[76:79]
	v_mfma_f32_16x16x32_bf16 v[72:75], v[152:155], v[222:225], v[72:75]
	v_mfma_f32_16x16x32_bf16 v[116:119], v[156:159], v[184:187], v[116:119]
	v_mfma_f32_16x16x32_bf16 v[112:115], v[170:173], v[184:187], v[112:115]
	v_mfma_f32_16x16x32_bf16 v[100:103], v[156:159], v[192:195], v[100:103]
	v_mfma_f32_16x16x32_bf16 v[96:99], v[170:173], v[192:195], v[96:99]
	v_mfma_f32_16x16x32_bf16 v[84:87], v[156:159], v[200:203], v[84:87]
	v_mfma_f32_16x16x32_bf16 v[80:83], v[170:173], v[200:203], v[80:83]
	v_mfma_f32_16x16x32_bf16 v[68:71], v[156:159], v[218:221], v[68:71]
	v_mfma_f32_16x16x32_bf16 v[64:67], v[170:173], v[218:221], v[64:67]
	v_mfma_f32_16x16x32_bf16 v[116:119], v[160:163], v[188:191], v[116:119]
	v_mfma_f32_16x16x32_bf16 v[112:115], v[180:183], v[188:191], v[112:115]
	v_mfma_f32_16x16x32_bf16 v[100:103], v[160:163], v[196:199], v[100:103]
	v_mfma_f32_16x16x32_bf16 v[96:99], v[180:183], v[196:199], v[96:99]
	v_mfma_f32_16x16x32_bf16 v[84:87], v[160:163], v[204:207], v[84:87]
	v_mfma_f32_16x16x32_bf16 v[80:83], v[180:183], v[204:207], v[80:83]
	v_mfma_f32_16x16x32_bf16 v[68:71], v[160:163], v[222:225], v[68:71]
	v_mfma_f32_16x16x32_bf16 v[64:67], v[180:183], v[222:225], v[64:67]
	s_setprio 0
	s_barrier
; #define PG8_STAGE(bufoff, gbase, voff) do { _Pragma("unroll") for (int _i = 0; _i < 2; ++_i) \
;         __builtin_amdgcn_global_load_lds((const unsigned*)((const char*)(gbase) + (voff)[_i]), (PG8_LAS unsigned*)(lds + (bufoff) + ldsw + _i * 8192), 16, 0, 0); } while (0)
; #define PG8_LDA(dst, b, h) do { _Pragma("unroll") for (int m = 0; m < 4; ++m) _Pragma("unroll") for (int k = 0; k < 2; ++k) dst[m][k] = *(const PG8_LAS bf16x8*)(lds + PG8_SA(b, h) + aoff + m * 2048 + k * 1024); } while (0)
; #define PG8_MMA(ai, bj, At, Bt) do { __builtin_amdgcn_s_setprio(1); _Pragma("unroll") for (int m = 0; m < 4; ++m) _Pragma("unroll") for (int n = 0; n < 2; ++n) _Pragma("unroll") for (int k = 0; k < 2; ++k) \
;         acc[ai][bj][m][n] = __builtin_amdgcn_mfma_f32_16x16x32_bf16(Bt[n][k], At[m][k], acc[ai][bj][m][n], 0, 0, 0); __builtin_amdgcn_s_setprio(0); } while (0)
; #define PG8_WAIT_V(n) asm volatile("s_waitcnt vmcnt(" #n ")" ::: "memory")
; #define PG8_WAIT_L(n) asm volatile("s_waitcnt lgkmcnt(" #n ")" ::: "memory")
; #define PG8_BAR __builtin_amdgcn_s_barrier()
; #define PG8_SCHED __builtin_amdgcn_sched_barrier(0)
; template <class Epi, class Sched, bool ALIGN_EPI = false, bool SP2 = false>
; __device__ __forceinline__ void gemm_phase(PG8_LAS unsigned char* lds, const Gemm g, const Sched& S, const Epi& E) {
;     ...
;         for (int t = 0; t < nt; t += 2) {
;             const bool last = (t == nt - 2);
;             const char* a1 = cA + (size_t)(t + 1) * kstep;
;             const char* a2 = last ? nA : cA + (size_t)(t + 2) * kstep; const char* b2 = last ? nB : cB + (size_t)(t + 2) * kstep;
;             const char* a3 = a2 + kstep; const char* b3 = b2 + kstep;
;     ...
;             PG8_LDA(At, 1, 1); PG8_STAGE(PG8_SB(1, 0), b3, voffB); PG8_STAGE(PG8_SB(1, 1), b3 + hstep, voffB); PG8_STAGE(PG8_SA(1, 0), a3, voffA);
;             PG8_WAIT_V(8); PG8_WAIT_L(0); PG8_BAR; PG8_MMA(1, 0, At, B0); PG8_MMA(1, 1, At, B1); PG8_BAR; PG8_SCHED;
	s_add_i32 s48, s56, s8
	v_lshl_add_u64 v[176:177], v[176:177], 0, s[4:5]
	s_mov_b32 m0, s48
	ds_read_b128 v[184:187], v168 offset:49152
	ds_read_b128 v[188:191], v168 offset:50176
	ds_read_b128 v[192:195], v168 offset:51200
	ds_read_b128 v[196:199], v168 offset:52224
	ds_read_b128 v[200:203], v168 offset:53248
	ds_read_b128 v[204:207], v168 offset:54272
	ds_read_b128 v[218:221], v168 offset:55296
	ds_read_b128 v[222:225], v168 offset:56320
	global_load_lds_dwordx4 v[176:177], off
	s_add_i32 m0, s48, 0x2000
	s_add_u32 s46, s46, 0x40080
	v_lshl_add_u64 v[176:177], v[178:179], 0, s[4:5]
	s_addc_u32 s47, s47, 0
	s_add_i32 s48, s57, s8
	global_load_lds_dwordx4 v[176:177], off
	v_lshl_add_u64 v[176:177], s[46:47], 0, v[174:175]
	s_mov_b32 m0, s48
	s_nop 0
	global_load_lds_dwordx4 v[176:177], off
	v_lshl_add_u64 v[176:177], s[46:47], 0, v[136:137]
	s_add_i32 m0, s48, 0x2000
	s_nop 0
	global_load_lds_dwordx4 v[176:177], off
	v_lshl_add_u64 v[176:177], v[208:209], 0, s[4:5]
	s_mov_b32 m0, s93
	s_nop 0
	global_load_lds_dwordx4 v[176:177], off
	v_lshl_add_u64 v[176:177], v[226:227], 0, s[4:5]
	s_mov_b32 m0, s66
	s_nop 0
	global_load_lds_dwordx4 v[176:177], off
	s_waitcnt vmcnt(8)
	s_waitcnt lgkmcnt(0)
	s_barrier
	s_setprio 1
	s_waitcnt lgkmcnt(0)
	v_mfma_f32_16x16x32_bf16 v[60:63], v[128:131], v[184:187], v[60:63]
	v_mfma_f32_16x16x32_bf16 v[56:59], v[148:151], v[184:187], v[56:59]
	v_mfma_f32_16x16x32_bf16 v[44:47], v[128:131], v[192:195], v[44:47]
	v_mfma_f32_16x16x32_bf16 v[40:43], v[148:151], v[192:195], v[40:43]
	v_mfma_f32_16x16x32_bf16 v[28:31], v[128:131], v[200:203], v[28:31]
	v_mfma_f32_16x16x32_bf16 v[24:27], v[148:151], v[200:203], v[24:27]
	v_mfma_f32_16x16x32_bf16 v[12:15], v[128:131], v[218:221], v[12:15]
	v_mfma_f32_16x16x32_bf16 v[8:11], v[148:151], v[218:221], v[8:11]
	v_mfma_f32_16x16x32_bf16 v[60:63], v[144:147], v[188:191], v[60:63]
	v_mfma_f32_16x16x32_bf16 v[56:59], v[152:155], v[188:191], v[56:59]
	v_mfma_f32_16x16x32_bf16 v[44:47], v[144:147], v[196:199], v[44:47]
	v_mfma_f32_16x16x32_bf16 v[40:43], v[152:155], v[196:199], v[40:43]
	v_mfma_f32_16x16x32_bf16 v[28:31], v[144:147], v[204:207], v[28:31]
	v_mfma_f32_16x16x32_bf16 v[24:27], v[152:155], v[204:207], v[24:27]
	v_mfma_f32_16x16x32_bf16 v[12:15], v[144:147], v[222:225], v[12:15]
	v_mfma_f32_16x16x32_bf16 v[8:11], v[152:155], v[222:225], v[8:11]
	v_mfma_f32_16x16x32_bf16 v[52:55], v[156:159], v[184:187], v[52:55]
	v_mfma_f32_16x16x32_bf16 v[48:51], v[170:173], v[184:187], v[48:51]
	v_mfma_f32_16x16x32_bf16 v[36:39], v[156:159], v[192:195], v[36:39]
	v_mfma_f32_16x16x32_bf16 v[32:35], v[170:173], v[192:195], v[32:35]
	v_mfma_f32_16x16x32_bf16 v[20:23], v[156:159], v[200:203], v[20:23]
	v_mfma_f32_16x16x32_bf16 v[16:19], v[170:173], v[200:203], v[16:19]
	v_mfma_f32_16x16x32_bf16 v[4:7], v[156:159], v[218:221], v[4:7]
	v_mfma_f32_16x16x32_bf16 v[0:3], v[170:173], v[218:221], v[0:3]
	v_mfma_f32_16x16x32_bf16 v[52:55], v[160:163], v[188:191], v[52:55]
	v_mfma_f32_16x16x32_bf16 v[48:51], v[180:183], v[188:191], v[48:51]
	v_mfma_f32_16x16x32_bf16 v[36:39], v[160:163], v[196:199], v[36:39]
	v_mfma_f32_16x16x32_bf16 v[32:35], v[180:183], v[196:199], v[32:35]
	v_mfma_f32_16x16x32_bf16 v[20:23], v[160:163], v[204:207], v[20:23]
	v_mfma_f32_16x16x32_bf16 v[16:19], v[180:183], v[204:207], v[16:19]
	v_mfma_f32_16x16x32_bf16 v[4:7], v[160:163], v[222:225], v[4:7]
	v_mfma_f32_16x16x32_bf16 v[0:3], v[180:183], v[222:225], v[0:3]
	s_setprio 0
	s_barrier
	s_add_i32 vcc_lo, vcc_lo, 2
	s_add_u32 s38, s38, 0x100
	s_addc_u32 s39, s39, 0
	s_add_u32 s71, s71, 0x100
	s_addc_u32 s73, s73, 0
	s_cmp_gt_u32 vcc_lo, 13
	s_cbranch_scc0 .LBB0_219

; #define PG8_STAGE(bufoff, gbase, voff) do { _Pragma("unroll") for (int _i = 0; _i < 2; ++_i) \
;         __builtin_amdgcn_global_load_lds((const unsigned*)((const char*)(gbase) + (voff)[_i]), (PG8_LAS unsigned*)(lds + (bufoff) + ldsw + _i * 8192), 16, 0, 0); } while (0)
; #define PG8_WAIT_V(n) asm volatile("s_waitcnt vmcnt(" #n ")" ::: "memory")
; #define PG8_WAIT_L(n) asm volatile("s_waitcnt lgkmcnt(" #n ")" ::: "memory")
; #define PG8_BAR __builtin_amdgcn_s_barrier()
; template <class Epi, class Sched, bool ALIGN_EPI = false, bool SP2 = false>
; __device__ __forceinline__ void gemm_phase(PG8_LAS unsigned char* lds, const Gemm g, const Sched& S, const Epi& E) {
;     ...
;         const bool has_next = S.next(ui + 1, nxt);
;         const char* nA = has_next ? (const char*)g.A + (size_t)nxt.pm * tstep + (size_t)nxt.pn * g.a_gs : cA; const char* nB = has_next ? (const char*)g.Bt + (size_t)nxt.pn * tstep : cB;
;         for (int t = 0; t < nt; t += 2) {
;             const bool last = (t == nt - 2);
;             const char* a1 = cA + (size_t)(t + 1) * kstep;
;             const char* a2 = last ? nA : cA + (size_t)(t + 2) * kstep; const char* b2 = last ? nB : cB + (size_t)(t + 2) * kstep;
;             const char* a3 = a2 + kstep; const char* b3 = b2 + kstep;
;             if (last && has_next) S.a_ready(nxt);
;             if constexpr (SP2) {
;             PG8_LDB(B0, 0, 0); PG8_LDB(B1, 0, 1); PG8_SCHED; PG8_LDA(At, 0, 0); PG8_STAGE(PG8_SA(1, 1), a1 + hstep, voffA);
;             PG8_WAIT_V(8); PG8_WAIT_L(0); PG8_BAR; PG8_MMA(0, 0, At, B0); PG8_MMA(0, 1, At, B1); PG8_BAR; PG8_SCHED;
;             PG8_LDA(At, 0, 1); PG8_STAGE(PG8_SB(0, 0), b2, voffB); PG8_STAGE(PG8_SB(0, 1), b2 + hstep, voffB); PG8_STAGE(PG8_SA(0, 0), a2, voffA);
;             PG8_WAIT_V(8); PG8_WAIT_L(0); PG8_BAR; PG8_MMA(1, 0, At, B0); PG8_MMA(1, 1, At, B1); PG8_BAR; PG8_SCHED;
;             PG8_LDB(B0, 1, 0); PG8_LDB(B1, 1, 1); PG8_SCHED; PG8_LDA(At, 1, 0); PG8_STAGE(PG8_SA(0, 1), a2 + hstep, voffA);
;             PG8_WAIT_V(8); PG8_WAIT_L(0); PG8_BAR; PG8_MMA(0, 0, At, B0); PG8_MMA(0, 1, At, B1); PG8_BAR; PG8_SCHED;
;             PG8_LDA(At, 1, 1); PG8_STAGE(PG8_SB(1, 0), b3, voffB); PG8_STAGE(PG8_SB(1, 1), b3 + hstep, voffB); PG8_STAGE(PG8_SA(1, 0), a3, voffA);
;             PG8_WAIT_V(8); PG8_WAIT_L(0); PG8_BAR; PG8_MMA(1, 0, At, B0); PG8_MMA(1, 1, At, B1); PG8_BAR; PG8_SCHED;
.LBB0_1640:
	s_add_u32 s0, s0, 0x80
	s_addc_u32 s1, s1, 0
	s_add_u32 s44, s38, 0x100
	s_addc_u32 s45, s39, 0
	s_mov_b32 s38, 0
	s_add_i32 s78, s38, 2
	s_add_u32 s79, s0, 0x80
	s_addc_u32 s39, s1, 0
	s_add_i32 s93, 0, 0x10000
	s_cmp_eq_u32 s75, s38
	s_cselect_b32 s39, s63, s39
	s_cselect_b32 s38, s62, s79
	s_cselect_b32 s95, s65, s45
	s_cselect_b32 s94, s64, s44
	s_add_i32 s79, 0, 0x14000
	v_add_u32_e32 v68, s93, v218
	v_add_u32_e32 v156, s79, v218
	ds_read_b128 v[56:59], v68
	ds_read_b128 v[60:63], v68 offset:1024
	ds_read_b128 v[64:67], v68 offset:2048
	ds_read_b128 v[68:71], v68 offset:3072
	ds_read_b128 v[144:147], v156
	ds_read_b128 v[148:151], v156 offset:1024
	ds_read_b128 v[152:155], v156 offset:2048
	ds_read_b128 v[156:159], v156 offset:3072
	v_lshl_add_u64 v[172:173], s[0:1], 0, v[186:187]
	s_add_i32 m0, s9, 0xc000
	ds_read_b128 v[160:163], v220
	ds_read_b128 v[164:167], v220 offset:1024
	ds_read_b128 v[168:171], v220 offset:2048
	ds_read_b128 v[176:179], v220 offset:3072
	ds_read_b128 v[190:193], v220 offset:4096
	ds_read_b128 v[194:197], v220 offset:5120
	ds_read_b128 v[198:201], v220 offset:6144
	ds_read_b128 v[202:205], v220 offset:7168
	global_load_lds_dwordx4 v[172:173], off
	v_lshl_add_u64 v[172:173], s[0:1], 0, v[188:189]
	s_add_i32 m0, s9, 0xe000
	s_nop 0
	global_load_lds_dwordx4 v[172:173], off
	s_waitcnt vmcnt(8)
	s_waitcnt lgkmcnt(0)
	s_barrier
	s_setprio 1
	s_waitcnt lgkmcnt(0)
	v_mfma_f32_16x16x32_bf16 v[140:143], v[56:59], v[160:163], 0
	v_mfma_f32_16x16x32_bf16 v[136:139], v[64:67], v[160:163], 0
	v_mfma_f32_16x16x32_bf16 v[124:127], v[56:59], v[168:171], 0
	v_mfma_f32_16x16x32_bf16 v[120:123], v[64:67], v[168:171], 0
	v_mfma_f32_16x16x32_bf16 v[108:111], v[56:59], v[190:193], 0
	v_mfma_f32_16x16x32_bf16 v[104:107], v[64:67], v[190:193], 0
	v_mfma_f32_16x16x32_bf16 v[92:95], v[56:59], v[198:201], 0
	v_mfma_f32_16x16x32_bf16 v[88:91], v[64:67], v[198:201], 0
	v_mfma_f32_16x16x32_bf16 v[140:143], v[60:63], v[164:167], v[140:143]
	v_mfma_f32_16x16x32_bf16 v[136:139], v[68:71], v[164:167], v[136:139]
	v_mfma_f32_16x16x32_bf16 v[124:127], v[60:63], v[176:179], v[124:127]
	v_mfma_f32_16x16x32_bf16 v[120:123], v[68:71], v[176:179], v[120:123]
	v_mfma_f32_16x16x32_bf16 v[108:111], v[60:63], v[194:197], v[108:111]
	v_mfma_f32_16x16x32_bf16 v[104:107], v[68:71], v[194:197], v[104:107]
	v_mfma_f32_16x16x32_bf16 v[92:95], v[60:63], v[202:205], v[92:95]
	v_mfma_f32_16x16x32_bf16 v[88:91], v[68:71], v[202:205], v[88:91]
	v_mfma_f32_16x16x32_bf16 v[132:135], v[144:147], v[160:163], 0
	v_mfma_f32_16x16x32_bf16 v[128:131], v[152:155], v[160:163], 0
	v_mfma_f32_16x16x32_bf16 v[116:119], v[144:147], v[168:171], 0
	v_mfma_f32_16x16x32_bf16 v[112:115], v[152:155], v[168:171], 0
	v_mfma_f32_16x16x32_bf16 v[100:103], v[144:147], v[190:193], 0
	v_mfma_f32_16x16x32_bf16 v[96:99], v[152:155], v[190:193], 0
	v_mfma_f32_16x16x32_bf16 v[84:87], v[144:147], v[198:201], 0
	v_mfma_f32_16x16x32_bf16 v[80:83], v[152:155], v[198:201], 0
	v_mfma_f32_16x16x32_bf16 v[132:135], v[148:151], v[164:167], v[132:135]
	v_mfma_f32_16x16x32_bf16 v[128:131], v[156:159], v[164:167], v[128:131]
	v_mfma_f32_16x16x32_bf16 v[116:119], v[148:151], v[176:179], v[116:119]
	v_mfma_f32_16x16x32_bf16 v[112:115], v[156:159], v[176:179], v[112:115]
	v_mfma_f32_16x16x32_bf16 v[100:103], v[148:151], v[194:197], v[100:103]
	v_mfma_f32_16x16x32_bf16 v[96:99], v[156:159], v[194:197], v[96:99]
	v_mfma_f32_16x16x32_bf16 v[84:87], v[148:151], v[202:205], v[84:87]
	v_mfma_f32_16x16x32_bf16 v[80:83], v[156:159], v[202:205], v[80:83]
	s_setprio 0
	s_barrier
	s_add_i32 s93, s93, s8
	v_lshl_add_u64 v[172:173], s[94:95], 0, v[174:175]
	s_mov_b32 m0, s93
	ds_read_b128 v[160:163], v220 offset:16384
	ds_read_b128 v[164:167], v220 offset:17408
	ds_read_b128 v[168:171], v220 offset:18432
	ds_read_b128 v[176:179], v220 offset:19456
	ds_read_b128 v[190:193], v220 offset:20480
	ds_read_b128 v[194:197], v220 offset:21504
	ds_read_b128 v[198:201], v220 offset:22528
	ds_read_b128 v[202:205], v220 offset:23552
	global_load_lds_dwordx4 v[172:173], off
	s_add_i32 m0, s93, 0x2000
	v_lshl_add_u64 v[206:207], s[94:95], 0, v[180:181]
	s_add_u32 s94, s94, s50
	s_addc_u32 s95, s95, 0
	s_add_i32 s79, s79, s8
	global_load_lds_dwordx4 v[206:207], off
	v_lshl_add_u64 v[208:209], s[94:95], 0, v[174:175]
	s_mov_b32 m0, s79
	v_lshl_add_u64 v[222:223], s[94:95], 0, v[180:181]
	global_load_lds_dwordx4 v[208:209], off
	s_add_i32 m0, s79, 0x2000
	v_lshl_add_u64 v[224:225], s[38:39], 0, v[184:185]
	global_load_lds_dwordx4 v[222:223], off
	s_mov_b32 m0, s9
	v_lshl_add_u64 v[226:227], s[38:39], 0, v[182:183]
	global_load_lds_dwordx4 v[224:225], off
	s_mov_b32 m0, s67
	s_nop 0
	global_load_lds_dwordx4 v[226:227], off
	s_waitcnt vmcnt(8)
	s_waitcnt lgkmcnt(0)
	s_barrier
; #define PG8_STAGE(bufoff, gbase, voff) do { _Pragma("unroll") for (int _i = 0; _i < 2; ++_i) \
;         __builtin_amdgcn_global_load_lds((const unsigned*)((const char*)(gbase) + (voff)[_i]), (PG8_LAS unsigned*)(lds + (bufoff) + ldsw + _i * 8192), 16, 0, 0); } while (0)
; #define PG8_LDA(dst, b, h) do { _Pragma("unroll") for (int m = 0; m < 4; ++m) _Pragma("unroll") for (int k = 0; k < 2; ++k) dst[m][k] = *(const PG8_LAS bf16x8*)(lds + PG8_SA(b, h) + aoff + m * 2048 + k * 1024); } while (0)
; #define PG8_LDB(dst, b, h) do { _Pragma("unroll") for (int n = 0; n < 2; ++n) _Pragma("unroll") for (int k = 0; k < 2; ++k) dst[n][k] = *(const PG8_LAS bf16x8*)(lds + PG8_SB(b, h) + boff + n * 2048 + k * 1024); } while (0)
; #define PG8_MMA(ai, bj, At, Bt) do { __builtin_amdgcn_s_setprio(1); _Pragma("unroll") for (int m = 0; m < 4; ++m) _Pragma("unroll") for (int n = 0; n < 2; ++n) _Pragma("unroll") for (int k = 0; k < 2; ++k) \
;         acc[ai][bj][m][n] = __builtin_amdgcn_mfma_f32_16x16x32_bf16(Bt[n][k], At[m][k], acc[ai][bj][m][n], 0, 0, 0); __builtin_amdgcn_s_setprio(0); } while (0)
; #define PG8_WAIT_V(n) asm volatile("s_waitcnt vmcnt(" #n ")" ::: "memory")
; #define PG8_WAIT_L(n) asm volatile("s_waitcnt lgkmcnt(" #n ")" ::: "memory")
; #define PG8_BAR __builtin_amdgcn_s_barrier()
; #define PG8_SCHED __builtin_amdgcn_sched_barrier(0)
; template <class Epi, class Sched, bool ALIGN_EPI = false, bool SP2 = false>
; __device__ __forceinline__ void gemm_phase(PG8_LAS unsigned char* lds, const Gemm g, const Sched& S, const Epi& E) {
;     ...
;             PG8_WAIT_V(8); PG8_WAIT_L(0); PG8_BAR; PG8_MMA(1, 0, At, B0); PG8_MMA(1, 1, At, B1); PG8_BAR; PG8_SCHED;
;             PG8_LDB(B0, 1, 0); PG8_LDB(B1, 1, 1); PG8_SCHED; PG8_LDA(At, 1, 0); PG8_STAGE(PG8_SA(0, 1), a2 + hstep, voffA);
;             PG8_WAIT_V(8); PG8_WAIT_L(0); PG8_BAR; PG8_MMA(0, 0, At, B0); PG8_MMA(0, 1, At, B1); PG8_BAR; PG8_SCHED;
	s_setprio 1
	s_waitcnt lgkmcnt(0)
	v_mfma_f32_16x16x32_bf16 v[76:79], v[56:59], v[160:163], 0
	v_mfma_f32_16x16x32_bf16 v[72:75], v[64:67], v[160:163], 0
	v_mfma_f32_16x16x32_bf16 v[44:47], v[56:59], v[168:171], 0
	v_mfma_f32_16x16x32_bf16 v[40:43], v[64:67], v[168:171], 0
	v_mfma_f32_16x16x32_bf16 v[28:31], v[56:59], v[190:193], 0
	v_mfma_f32_16x16x32_bf16 v[24:27], v[64:67], v[190:193], 0
	v_mfma_f32_16x16x32_bf16 v[12:15], v[56:59], v[198:201], 0
	v_mfma_f32_16x16x32_bf16 v[8:11], v[64:67], v[198:201], 0
	v_mfma_f32_16x16x32_bf16 v[76:79], v[60:63], v[164:167], v[76:79]
	v_mfma_f32_16x16x32_bf16 v[72:75], v[68:71], v[164:167], v[72:75]
	v_mfma_f32_16x16x32_bf16 v[44:47], v[60:63], v[176:179], v[44:47]
	v_mfma_f32_16x16x32_bf16 v[40:43], v[68:71], v[176:179], v[40:43]
	v_mfma_f32_16x16x32_bf16 v[28:31], v[60:63], v[194:197], v[28:31]
	v_mfma_f32_16x16x32_bf16 v[24:27], v[68:71], v[194:197], v[24:27]
	v_mfma_f32_16x16x32_bf16 v[12:15], v[60:63], v[202:205], v[12:15]
	v_mfma_f32_16x16x32_bf16 v[8:11], v[68:71], v[202:205], v[8:11]
	v_mfma_f32_16x16x32_bf16 v[52:55], v[144:147], v[160:163], 0
	v_mfma_f32_16x16x32_bf16 v[48:51], v[152:155], v[160:163], 0
	v_mfma_f32_16x16x32_bf16 v[36:39], v[144:147], v[168:171], 0
	v_mfma_f32_16x16x32_bf16 v[32:35], v[152:155], v[168:171], 0
	v_mfma_f32_16x16x32_bf16 v[20:23], v[144:147], v[190:193], 0
	v_mfma_f32_16x16x32_bf16 v[16:19], v[152:155], v[190:193], 0
	v_mfma_f32_16x16x32_bf16 v[4:7], v[144:147], v[198:201], 0
	v_mfma_f32_16x16x32_bf16 v[0:3], v[152:155], v[198:201], 0
	v_mfma_f32_16x16x32_bf16 v[52:55], v[148:151], v[164:167], v[52:55]
	v_mfma_f32_16x16x32_bf16 v[48:51], v[156:159], v[164:167], v[48:51]
	v_mfma_f32_16x16x32_bf16 v[36:39], v[148:151], v[176:179], v[36:39]
	v_mfma_f32_16x16x32_bf16 v[32:35], v[156:159], v[176:179], v[32:35]
	v_mfma_f32_16x16x32_bf16 v[20:23], v[148:151], v[194:197], v[20:23]
	v_mfma_f32_16x16x32_bf16 v[16:19], v[156:159], v[194:197], v[16:19]
	v_mfma_f32_16x16x32_bf16 v[4:7], v[148:151], v[202:205], v[4:7]
	v_mfma_f32_16x16x32_bf16 v[0:3], v[156:159], v[202:205], v[0:3]
	s_setprio 0
	s_barrier
	s_add_i32 s79, 0, 0x18000
	s_add_i32 s93, 0, 0x1c000
	v_add_u32_e32 v68, s79, v218
	v_add_u32_e32 v156, s93, v218
	ds_read_b128 v[56:59], v68
	ds_read_b128 v[60:63], v68 offset:1024
	ds_read_b128 v[64:67], v68 offset:2048
	ds_read_b128 v[68:71], v68 offset:3072
	ds_read_b128 v[144:147], v156
	ds_read_b128 v[148:151], v156 offset:1024
	ds_read_b128 v[152:155], v156 offset:2048
	ds_read_b128 v[156:159], v156 offset:3072
	s_add_u32 s38, s38, s50
	s_addc_u32 s39, s39, 0
	s_mov_b32 m0, s68
	v_lshl_add_u64 v[228:229], s[38:39], 0, v[184:185]
	ds_read_b128 v[160:163], v220 offset:32768
	ds_read_b128 v[164:167], v220 offset:33792
	ds_read_b128 v[168:171], v220 offset:34816
	ds_read_b128 v[176:179], v220 offset:35840
	ds_read_b128 v[190:193], v220 offset:36864
	ds_read_b128 v[194:197], v220 offset:37888
	ds_read_b128 v[198:201], v220 offset:38912
	ds_read_b128 v[202:205], v220 offset:39936
	global_load_lds_dwordx4 v[228:229], off
	v_lshl_add_u64 v[228:229], s[38:39], 0, v[182:183]
	s_mov_b32 m0, s69
	s_nop 0
	global_load_lds_dwordx4 v[228:229], off
	s_waitcnt vmcnt(8)
	s_waitcnt lgkmcnt(0)
	s_barrier
	s_setprio 1
	s_waitcnt lgkmcnt(0)
	v_mfma_f32_16x16x32_bf16 v[140:143], v[56:59], v[160:163], v[140:143]
	v_mfma_f32_16x16x32_bf16 v[136:139], v[64:67], v[160:163], v[136:139]
	v_mfma_f32_16x16x32_bf16 v[124:127], v[56:59], v[168:171], v[124:127]
	v_mfma_f32_16x16x32_bf16 v[120:123], v[64:67], v[168:171], v[120:123]
	v_mfma_f32_16x16x32_bf16 v[108:111], v[56:59], v[190:193], v[108:111]
	v_mfma_f32_16x16x32_bf16 v[104:107], v[64:67], v[190:193], v[104:107]
	v_mfma_f32_16x16x32_bf16 v[92:95], v[56:59], v[198:201], v[92:95]
	v_mfma_f32_16x16x32_bf16 v[88:91], v[64:67], v[198:201], v[88:91]
	v_mfma_f32_16x16x32_bf16 v[140:143], v[60:63], v[164:167], v[140:143]
	v_mfma_f32_16x16x32_bf16 v[136:139], v[68:71], v[164:167], v[136:139]
	v_mfma_f32_16x16x32_bf16 v[124:127], v[60:63], v[176:179], v[124:127]
	v_mfma_f32_16x16x32_bf16 v[120:123], v[68:71], v[176:179], v[120:123]
	v_mfma_f32_16x16x32_bf16 v[108:111], v[60:63], v[194:197], v[108:111]
	v_mfma_f32_16x16x32_bf16 v[104:107], v[68:71], v[194:197], v[104:107]
	v_mfma_f32_16x16x32_bf16 v[92:95], v[60:63], v[202:205], v[92:95]
	v_mfma_f32_16x16x32_bf16 v[88:91], v[68:71], v[202:205], v[88:91]
	v_mfma_f32_16x16x32_bf16 v[132:135], v[144:147], v[160:163], v[132:135]
	v_mfma_f32_16x16x32_bf16 v[128:131], v[152:155], v[160:163], v[128:131]
	v_mfma_f32_16x16x32_bf16 v[116:119], v[144:147], v[168:171], v[116:119]
	v_mfma_f32_16x16x32_bf16 v[112:115], v[152:155], v[168:171], v[112:115]
	v_mfma_f32_16x16x32_bf16 v[100:103], v[144:147], v[190:193], v[100:103]
	v_mfma_f32_16x16x32_bf16 v[96:99], v[152:155], v[190:193], v[96:99]
	v_mfma_f32_16x16x32_bf16 v[84:87], v[144:147], v[198:201], v[84:87]
	v_mfma_f32_16x16x32_bf16 v[80:83], v[152:155], v[198:201], v[80:83]
	v_mfma_f32_16x16x32_bf16 v[132:135], v[148:151], v[164:167], v[132:135]
	v_mfma_f32_16x16x32_bf16 v[128:131], v[156:159], v[164:167], v[128:131]
	v_mfma_f32_16x16x32_bf16 v[116:119], v[148:151], v[176:179], v[116:119]
	v_mfma_f32_16x16x32_bf16 v[112:115], v[156:159], v[176:179], v[112:115]
	v_mfma_f32_16x16x32_bf16 v[100:103], v[148:151], v[194:197], v[100:103]
	v_mfma_f32_16x16x32_bf16 v[96:99], v[156:159], v[194:197], v[96:99]
	v_mfma_f32_16x16x32_bf16 v[84:87], v[148:151], v[202:205], v[84:87]
	v_mfma_f32_16x16x32_bf16 v[80:83], v[156:159], v[202:205], v[80:83]
	s_setprio 0
	s_barrier
; #define PG8_STAGE(bufoff, gbase, voff) do { _Pragma("unroll") for (int _i = 0; _i < 2; ++_i) \
;         __builtin_amdgcn_global_load_lds((const unsigned*)((const char*)(gbase) + (voff)[_i]), (PG8_LAS unsigned*)(lds + (bufoff) + ldsw + _i * 8192), 16, 0, 0); } while (0)
; #define PG8_LDA(dst, b, h) do { _Pragma("unroll") for (int m = 0; m < 4; ++m) _Pragma("unroll") for (int k = 0; k < 2; ++k) dst[m][k] = *(const PG8_LAS bf16x8*)(lds + PG8_SA(b, h) + aoff + m * 2048 + k * 1024); } while (0)
; #define PG8_MMA(ai, bj, At, Bt) do { __builtin_amdgcn_s_setprio(1); _Pragma("unroll") for (int m = 0; m < 4; ++m) _Pragma("unroll") for (int n = 0; n < 2; ++n) _Pragma("unroll") for (int k = 0; k < 2; ++k) \
;         acc[ai][bj][m][n] = __builtin_amdgcn_mfma_f32_16x16x32_bf16(Bt[n][k], At[m][k], acc[ai][bj][m][n], 0, 0, 0); __builtin_amdgcn_s_setprio(0); } while (0)
; #define PG8_WAIT_V(n) asm volatile("s_waitcnt vmcnt(" #n ")" ::: "memory")
; #define PG8_WAIT_L(n) asm volatile("s_waitcnt lgkmcnt(" #n ")" ::: "memory")
; #define PG8_BAR __builtin_amdgcn_s_barrier()
; #define PG8_SCHED __builtin_amdgcn_sched_barrier(0)
; template <class Epi, class Sched, bool ALIGN_EPI = false, bool SP2 = false>
; __device__ __forceinline__ void gemm_phase(PG8_LAS unsigned char* lds, const Gemm g, const Sched& S, const Epi& E) {
;     ...
;         for (int t = 0; t < nt; t += 2) {
;             const bool last = (t == nt - 2);
;             const char* a1 = cA + (size_t)(t + 1) * kstep;
;             const char* a2 = last ? nA : cA + (size_t)(t + 2) * kstep; const char* b2 = last ? nB : cB + (size_t)(t + 2) * kstep;
;             const char* a3 = a2 + kstep; const char* b3 = b2 + kstep;
;     ...
;             PG8_LDA(At, 1, 1); PG8_STAGE(PG8_SB(1, 0), b3, voffB); PG8_STAGE(PG8_SB(1, 1), b3 + hstep, voffB); PG8_STAGE(PG8_SA(1, 0), a3, voffA);
;             PG8_WAIT_V(8); PG8_WAIT_L(0); PG8_BAR; PG8_MMA(1, 0, At, B0); PG8_MMA(1, 1, At, B1); PG8_BAR; PG8_SCHED;
	s_add_i32 s38, s79, s8
	v_lshl_add_u64 v[172:173], v[172:173], 0, s[4:5]
	s_mov_b32 m0, s38
	ds_read_b128 v[160:163], v220 offset:49152
	ds_read_b128 v[164:167], v220 offset:50176
	ds_read_b128 v[168:171], v220 offset:51200
	ds_read_b128 v[176:179], v220 offset:52224
	ds_read_b128 v[190:193], v220 offset:53248
	ds_read_b128 v[194:197], v220 offset:54272
	ds_read_b128 v[198:201], v220 offset:55296
	ds_read_b128 v[202:205], v220 offset:56320
	global_load_lds_dwordx4 v[172:173], off
	v_lshl_add_u64 v[172:173], v[206:207], 0, s[4:5]
	s_add_i32 m0, s38, 0x2000
	s_add_i32 s38, s93, s8
	global_load_lds_dwordx4 v[172:173], off
	v_lshl_add_u64 v[172:173], v[208:209], 0, s[4:5]
	s_mov_b32 m0, s38
	s_nop 0
	global_load_lds_dwordx4 v[172:173], off
	v_lshl_add_u64 v[172:173], v[222:223], 0, s[4:5]
	s_add_i32 m0, s38, 0x2000
	s_nop 0
	global_load_lds_dwordx4 v[172:173], off
	v_lshl_add_u64 v[172:173], v[224:225], 0, s[4:5]
	s_mov_b32 m0, s73
	s_nop 0
	global_load_lds_dwordx4 v[172:173], off
	v_lshl_add_u64 v[172:173], v[226:227], 0, s[4:5]
	s_mov_b32 m0, s74
	s_nop 0
	global_load_lds_dwordx4 v[172:173], off
	s_waitcnt vmcnt(8)
	s_waitcnt lgkmcnt(0)
	s_barrier
	s_setprio 1
	s_waitcnt lgkmcnt(0)
	v_mfma_f32_16x16x32_bf16 v[76:79], v[56:59], v[160:163], v[76:79]
	v_mfma_f32_16x16x32_bf16 v[72:75], v[64:67], v[160:163], v[72:75]
	v_mfma_f32_16x16x32_bf16 v[44:47], v[56:59], v[168:171], v[44:47]
	v_mfma_f32_16x16x32_bf16 v[40:43], v[64:67], v[168:171], v[40:43]
	v_mfma_f32_16x16x32_bf16 v[28:31], v[56:59], v[190:193], v[28:31]
	v_mfma_f32_16x16x32_bf16 v[24:27], v[64:67], v[190:193], v[24:27]
	v_mfma_f32_16x16x32_bf16 v[12:15], v[56:59], v[198:201], v[12:15]
	v_mfma_f32_16x16x32_bf16 v[8:11], v[64:67], v[198:201], v[8:11]
	v_mfma_f32_16x16x32_bf16 v[76:79], v[60:63], v[164:167], v[76:79]
	v_mfma_f32_16x16x32_bf16 v[72:75], v[68:71], v[164:167], v[72:75]
	v_mfma_f32_16x16x32_bf16 v[44:47], v[60:63], v[176:179], v[44:47]
	v_mfma_f32_16x16x32_bf16 v[40:43], v[68:71], v[176:179], v[40:43]
	v_mfma_f32_16x16x32_bf16 v[28:31], v[60:63], v[194:197], v[28:31]
	v_mfma_f32_16x16x32_bf16 v[24:27], v[68:71], v[194:197], v[24:27]
	v_mfma_f32_16x16x32_bf16 v[12:15], v[60:63], v[202:205], v[12:15]
	v_mfma_f32_16x16x32_bf16 v[8:11], v[68:71], v[202:205], v[8:11]
	v_mfma_f32_16x16x32_bf16 v[52:55], v[144:147], v[160:163], v[52:55]
	v_mfma_f32_16x16x32_bf16 v[48:51], v[152:155], v[160:163], v[48:51]
	v_mfma_f32_16x16x32_bf16 v[36:39], v[144:147], v[168:171], v[36:39]
	v_mfma_f32_16x16x32_bf16 v[32:35], v[152:155], v[168:171], v[32:35]
	v_mfma_f32_16x16x32_bf16 v[20:23], v[144:147], v[190:193], v[20:23]
	v_mfma_f32_16x16x32_bf16 v[16:19], v[152:155], v[190:193], v[16:19]
	v_mfma_f32_16x16x32_bf16 v[4:7], v[144:147], v[198:201], v[4:7]
	v_mfma_f32_16x16x32_bf16 v[0:3], v[152:155], v[198:201], v[0:3]
	v_mfma_f32_16x16x32_bf16 v[52:55], v[148:151], v[164:167], v[52:55]
	v_mfma_f32_16x16x32_bf16 v[48:51], v[156:159], v[164:167], v[48:51]
	v_mfma_f32_16x16x32_bf16 v[36:39], v[148:151], v[176:179], v[36:39]
	v_mfma_f32_16x16x32_bf16 v[32:35], v[156:159], v[176:179], v[32:35]
	v_mfma_f32_16x16x32_bf16 v[20:23], v[148:151], v[194:197], v[20:23]
	v_mfma_f32_16x16x32_bf16 v[16:19], v[156:159], v[194:197], v[16:19]
	v_mfma_f32_16x16x32_bf16 v[4:7], v[148:151], v[202:205], v[4:7]
	v_mfma_f32_16x16x32_bf16 v[0:3], v[156:159], v[202:205], v[0:3]
	s_setprio 0
	s_barrier
	s_add_u32 s0, s0, 0x100
	s_addc_u32 s1, s1, 0
	s_add_u32 s44, s44, 0x100
	s_addc_u32 s45, s45, 0
	s_cmp_ge_u32 s78, s72
	s_mov_b32 s38, s78
	s_cbranch_scc0 .LBB0_1641

; #define PG8_STAGE(bufoff, gbase, voff) do { _Pragma("unroll") for (int _i = 0; _i < 2; ++_i) \
;         __builtin_amdgcn_global_load_lds((const unsigned*)((const char*)(gbase) + (voff)[_i]), (PG8_LAS unsigned*)(lds + (bufoff) + ldsw + _i * 8192), 16, 0, 0); } while (0)
; #define PG8_WAIT_V(n) asm volatile("s_waitcnt vmcnt(" #n ")" ::: "memory")
; #define PG8_WAIT_L(n) asm volatile("s_waitcnt lgkmcnt(" #n ")" ::: "memory")
; template <class Epi, class Sched, bool ALIGN_EPI = false, bool SP2 = false>
; __device__ __forceinline__ void gemm_phase(PG8_LAS unsigned char* lds, const Gemm g, const Sched& S, const Epi& E) {
;     ...
;         const bool has_next = S.next(ui + 1, nxt);
;         const char* nA = has_next ? (const char*)g.A + (size_t)nxt.pm * tstep + (size_t)nxt.pn * g.a_gs : cA; const char* nB = has_next ? (const char*)g.Bt + (size_t)nxt.pn * tstep : cB;
;         for (int t = 0; t < nt; t += 2) {
;             const bool last = (t == nt - 2);
;             const char* a1 = cA + (size_t)(t + 1) * kstep;
;             const char* a2 = last ? nA : cA + (size_t)(t + 2) * kstep; const char* b2 = last ? nB : cB + (size_t)(t + 2) * kstep;
;             const char* a3 = a2 + kstep; const char* b3 = b2 + kstep;
;             if (last && has_next) S.a_ready(nxt);
;             if constexpr (SP2) {
;             PG8_LDB(B0, 0, 0); PG8_LDB(B1, 0, 1); PG8_SCHED; PG8_LDA(At, 0, 0); PG8_STAGE(PG8_SA(1, 1), a1 + hstep, voffA);
;             PG8_WAIT_V(8); PG8_WAIT_L(0); PG8_BAR; PG8_MMA(0, 0, At, B0); PG8_MMA(0, 1, At, B1); PG8_BAR; PG8_SCHED;
;             PG8_LDA(At, 0, 1); PG8_STAGE(PG8_SB(0, 0), b2, voffB); PG8_STAGE(PG8_SB(0, 1), b2 + hstep, voffB); PG8_STAGE(PG8_SA(0, 0), a2, voffA);
;             PG8_WAIT_V(8); PG8_WAIT_L(0); PG8_BAR; PG8_MMA(1, 0, At, B0); PG8_MMA(1, 1, At, B1); PG8_BAR; PG8_SCHED;
;             PG8_LDB(B0, 1, 0); PG8_LDB(B1, 1, 1); PG8_SCHED; PG8_LDA(At, 1, 0); PG8_STAGE(PG8_SA(0, 1), a2 + hstep, voffA);
;             PG8_WAIT_V(8); PG8_WAIT_L(0); PG8_BAR; PG8_MMA(0, 0, At, B0); PG8_MMA(0, 1, At, B1); PG8_BAR; PG8_SCHED;
;     ...
; #pragma unroll
;         for (int a = 0; a < 2; ++a)
; #pragma unroll
;             for (int b = 0; b < 2; ++b)
; #pragma unroll
;                 for (int m = 0; m < 4; ++m)
; #pragma unroll
;                     for (int n = 0; n < 2; ++n) acc[a][b][m][n] = (f32x4){0.f, 0.f, 0.f, 0.f};
.LBB0_1751:
	s_ashr_i32 s51, s50, 31
	s_lshl_b64 s[52:53], s[50:51], 19
	s_add_u32 s52, s10, s52
	s_addc_u32 s53, s11, s53
	s_and_b64 s[54:55], s[42:43], exec
	s_cselect_b32 s51, s53, s1
	s_cselect_b32 s69, s52, s0
	s_ashr_i32 s49, s48, 31
	s_lshl_b64 s[54:55], s[48:49], 19
	s_add_u32 s54, s9, s54
	s_addc_u32 s55, s16, s55
	s_and_b64 s[56:57], s[42:43], exec
	s_cselect_b32 s49, s55, s39
	s_cselect_b32 s70, s54, s38
	s_add_u32 s0, s0, 0x40080
	s_addc_u32 s1, s1, 0
	s_add_u32 s71, s38, 0x100
	s_addc_u32 s72, s39, 0
	s_mov_b32 s73, -2
	s_add_u32 s38, s0, 0xfffc0080
	s_addc_u32 s39, s1, -1
	s_add_i32 s74, 0, 0x10000
	s_cmp_eq_u32 s73, 12
	s_cselect_b32 s57, s51, s39
	s_cselect_b32 s56, s69, s38
	v_add_u32_e32 v151, s74, v147
	s_cselect_b32 s39, s49, s72
	s_cselect_b32 s38, s70, s71
	s_add_i32 s76, 0, 0x14000
	ds_read_b128 v[138:141], v151
	ds_read_b128 v[142:145], v151 offset:1024
	ds_read_b128 v[152:155], v151 offset:2048
	ds_read_b128 v[156:159], v151 offset:3072
	v_add_u32_e32 v151, s76, v147
	ds_read_b128 v[160:163], v151
	ds_read_b128 v[164:167], v151 offset:1024
	ds_read_b128 v[168:171], v151 offset:2048
	ds_read_b128 v[176:179], v151 offset:3072
	v_lshl_add_u64 v[172:173], s[0:1], 0, v[134:135]
	s_add_i32 m0, s58, 0xc000
	ds_read_b128 v[180:183], v150
	ds_read_b128 v[184:187], v150 offset:1024
	ds_read_b128 v[188:191], v150 offset:2048
	ds_read_b128 v[192:195], v150 offset:3072
	ds_read_b128 v[196:199], v150 offset:4096
	ds_read_b128 v[200:203], v150 offset:5120
	ds_read_b128 v[204:207], v150 offset:6144
	ds_read_b128 v[218:221], v150 offset:7168
	global_load_lds_dwordx4 v[172:173], off
	v_lshl_add_u64 v[172:173], s[0:1], 0, v[136:137]
	s_add_i32 m0, s58, 0xe000
	s_nop 0
	global_load_lds_dwordx4 v[172:173], off
	s_waitcnt vmcnt(8)
	s_waitcnt lgkmcnt(0)
	s_barrier
	s_setprio 1
	s_waitcnt lgkmcnt(0)
	v_mfma_f32_16x16x32_bf16 v[124:127], v[138:141], v[180:183], 0
	v_mfma_f32_16x16x32_bf16 v[120:123], v[152:155], v[180:183], 0
	v_mfma_f32_16x16x32_bf16 v[108:111], v[138:141], v[188:191], 0
	v_mfma_f32_16x16x32_bf16 v[104:107], v[152:155], v[188:191], 0
	v_mfma_f32_16x16x32_bf16 v[92:95], v[138:141], v[196:199], 0
	v_mfma_f32_16x16x32_bf16 v[88:91], v[152:155], v[196:199], 0
	v_mfma_f32_16x16x32_bf16 v[76:79], v[138:141], v[204:207], 0
	v_mfma_f32_16x16x32_bf16 v[72:75], v[152:155], v[204:207], 0
	v_mfma_f32_16x16x32_bf16 v[124:127], v[142:145], v[184:187], v[124:127]
	v_mfma_f32_16x16x32_bf16 v[120:123], v[156:159], v[184:187], v[120:123]
	v_mfma_f32_16x16x32_bf16 v[108:111], v[142:145], v[192:195], v[108:111]
	v_mfma_f32_16x16x32_bf16 v[104:107], v[156:159], v[192:195], v[104:107]
	v_mfma_f32_16x16x32_bf16 v[92:95], v[142:145], v[200:203], v[92:95]
	v_mfma_f32_16x16x32_bf16 v[88:91], v[156:159], v[200:203], v[88:91]
	v_mfma_f32_16x16x32_bf16 v[76:79], v[142:145], v[218:221], v[76:79]
	v_mfma_f32_16x16x32_bf16 v[72:75], v[156:159], v[218:221], v[72:75]
	v_mfma_f32_16x16x32_bf16 v[116:119], v[160:163], v[180:183], 0
	v_mfma_f32_16x16x32_bf16 v[112:115], v[168:171], v[180:183], 0
	v_mfma_f32_16x16x32_bf16 v[100:103], v[160:163], v[188:191], 0
	v_mfma_f32_16x16x32_bf16 v[96:99], v[168:171], v[188:191], 0
	v_mfma_f32_16x16x32_bf16 v[84:87], v[160:163], v[196:199], 0
	v_mfma_f32_16x16x32_bf16 v[80:83], v[168:171], v[196:199], 0
	v_mfma_f32_16x16x32_bf16 v[68:71], v[160:163], v[204:207], 0
	v_mfma_f32_16x16x32_bf16 v[64:67], v[168:171], v[204:207], 0
	v_mfma_f32_16x16x32_bf16 v[116:119], v[164:167], v[184:187], v[116:119]
	v_mfma_f32_16x16x32_bf16 v[112:115], v[176:179], v[184:187], v[112:115]
	v_mfma_f32_16x16x32_bf16 v[100:103], v[164:167], v[192:195], v[100:103]
	v_mfma_f32_16x16x32_bf16 v[96:99], v[176:179], v[192:195], v[96:99]
	v_mfma_f32_16x16x32_bf16 v[84:87], v[164:167], v[200:203], v[84:87]
	v_mfma_f32_16x16x32_bf16 v[80:83], v[176:179], v[200:203], v[80:83]
	v_mfma_f32_16x16x32_bf16 v[68:71], v[164:167], v[218:221], v[68:71]
	v_mfma_f32_16x16x32_bf16 v[64:67], v[176:179], v[218:221], v[64:67]
	s_setprio 0
	s_barrier
	s_add_i32 s74, s74, s8
	v_lshl_add_u64 v[172:173], s[38:39], 0, v[174:175]
	s_mov_b32 m0, s74
	ds_read_b128 v[180:183], v150 offset:16384
	ds_read_b128 v[184:187], v150 offset:17408
	ds_read_b128 v[188:191], v150 offset:18432
	ds_read_b128 v[192:195], v150 offset:19456
	ds_read_b128 v[196:199], v150 offset:20480
	ds_read_b128 v[200:203], v150 offset:21504
	ds_read_b128 v[204:207], v150 offset:22528
	ds_read_b128 v[218:221], v150 offset:23552
	global_load_lds_dwordx4 v[172:173], off
	s_add_i32 m0, s74, 0x2000
	s_add_u32 s74, s38, 0x40000
	v_lshl_add_u64 v[208:209], s[38:39], 0, v[128:129]
	s_addc_u32 s75, s39, 0
	s_add_i32 s76, s76, s8
	global_load_lds_dwordx4 v[208:209], off
	v_lshl_add_u64 v[222:223], s[74:75], 0, v[174:175]
	s_mov_b32 m0, s76
	v_lshl_add_u64 v[224:225], s[56:57], 0, v[130:131]
	global_load_lds_dwordx4 v[222:223], off
	v_lshl_add_u64 v[222:223], s[74:75], 0, v[128:129]
	s_add_i32 m0, s76, 0x2000
	s_nop 0
	global_load_lds_dwordx4 v[222:223], off
	v_lshl_add_u64 v[222:223], s[56:57], 0, v[132:133]
	s_mov_b32 m0, s58
	s_nop 0
	global_load_lds_dwordx4 v[222:223], off
	s_mov_b32 m0, s59
	s_nop 0
	global_load_lds_dwordx4 v[224:225], off
	s_waitcnt vmcnt(8)
	s_waitcnt lgkmcnt(0)
	s_barrier
; #define PG8_STAGE(bufoff, gbase, voff) do { _Pragma("unroll") for (int _i = 0; _i < 2; ++_i) \
;         __builtin_amdgcn_global_load_lds((const unsigned*)((const char*)(gbase) + (voff)[_i]), (PG8_LAS unsigned*)(lds + (bufoff) + ldsw + _i * 8192), 16, 0, 0); } while (0)
; #define PG8_LDA(dst, b, h) do { _Pragma("unroll") for (int m = 0; m < 4; ++m) _Pragma("unroll") for (int k = 0; k < 2; ++k) dst[m][k] = *(const PG8_LAS bf16x8*)(lds + PG8_SA(b, h) + aoff + m * 2048 + k * 1024); } while (0)
; #define PG8_LDB(dst, b, h) do { _Pragma("unroll") for (int n = 0; n < 2; ++n) _Pragma("unroll") for (int k = 0; k < 2; ++k) dst[n][k] = *(const PG8_LAS bf16x8*)(lds + PG8_SB(b, h) + boff + n * 2048 + k * 1024); } while (0)
; #define PG8_MMA(ai, bj, At, Bt) do { __builtin_amdgcn_s_setprio(1); _Pragma("unroll") for (int m = 0; m < 4; ++m) _Pragma("unroll") for (int n = 0; n < 2; ++n) _Pragma("unroll") for (int k = 0; k < 2; ++k) \
;         acc[ai][bj][m][n] = __builtin_amdgcn_mfma_f32_16x16x32_bf16(Bt[n][k], At[m][k], acc[ai][bj][m][n], 0, 0, 0); __builtin_amdgcn_s_setprio(0); } while (0)
; #define PG8_WAIT_V(n) asm volatile("s_waitcnt vmcnt(" #n ")" ::: "memory")
; #define PG8_WAIT_L(n) asm volatile("s_waitcnt lgkmcnt(" #n ")" ::: "memory")
; #define PG8_BAR __builtin_amdgcn_s_barrier()
; #define PG8_SCHED __builtin_amdgcn_sched_barrier(0)
; template <class Epi, class Sched, bool ALIGN_EPI = false, bool SP2 = false>
; __device__ __forceinline__ void gemm_phase(PG8_LAS unsigned char* lds, const Gemm g, const Sched& S, const Epi& E) {
;     ...
;             PG8_WAIT_V(8); PG8_WAIT_L(0); PG8_BAR; PG8_MMA(1, 0, At, B0); PG8_MMA(1, 1, At, B1); PG8_BAR; PG8_SCHED;
;             PG8_LDB(B0, 1, 0); PG8_LDB(B1, 1, 1); PG8_SCHED; PG8_LDA(At, 1, 0); PG8_STAGE(PG8_SA(0, 1), a2 + hstep, voffA);
;             PG8_WAIT_V(8); PG8_WAIT_L(0); PG8_BAR; PG8_MMA(0, 0, At, B0); PG8_MMA(0, 1, At, B1); PG8_BAR; PG8_SCHED;
	s_setprio 1
	s_waitcnt lgkmcnt(0)
	v_mfma_f32_16x16x32_bf16 v[60:63], v[138:141], v[180:183], 0
	v_mfma_f32_16x16x32_bf16 v[56:59], v[152:155], v[180:183], 0
	v_mfma_f32_16x16x32_bf16 v[44:47], v[138:141], v[188:191], 0
	v_mfma_f32_16x16x32_bf16 v[40:43], v[152:155], v[188:191], 0
	v_mfma_f32_16x16x32_bf16 v[28:31], v[138:141], v[196:199], 0
	v_mfma_f32_16x16x32_bf16 v[24:27], v[152:155], v[196:199], 0
	v_mfma_f32_16x16x32_bf16 v[12:15], v[138:141], v[204:207], 0
	v_mfma_f32_16x16x32_bf16 v[8:11], v[152:155], v[204:207], 0
	v_mfma_f32_16x16x32_bf16 v[60:63], v[142:145], v[184:187], v[60:63]
	v_mfma_f32_16x16x32_bf16 v[56:59], v[156:159], v[184:187], v[56:59]
	v_mfma_f32_16x16x32_bf16 v[44:47], v[142:145], v[192:195], v[44:47]
	v_mfma_f32_16x16x32_bf16 v[40:43], v[156:159], v[192:195], v[40:43]
	v_mfma_f32_16x16x32_bf16 v[28:31], v[142:145], v[200:203], v[28:31]
	v_mfma_f32_16x16x32_bf16 v[24:27], v[156:159], v[200:203], v[24:27]
	v_mfma_f32_16x16x32_bf16 v[12:15], v[142:145], v[218:221], v[12:15]
	v_mfma_f32_16x16x32_bf16 v[8:11], v[156:159], v[218:221], v[8:11]
	v_mfma_f32_16x16x32_bf16 v[52:55], v[160:163], v[180:183], 0
	v_mfma_f32_16x16x32_bf16 v[48:51], v[168:171], v[180:183], 0
	v_mfma_f32_16x16x32_bf16 v[36:39], v[160:163], v[188:191], 0
	v_mfma_f32_16x16x32_bf16 v[32:35], v[168:171], v[188:191], 0
	v_mfma_f32_16x16x32_bf16 v[20:23], v[160:163], v[196:199], 0
	v_mfma_f32_16x16x32_bf16 v[16:19], v[168:171], v[196:199], 0
	v_mfma_f32_16x16x32_bf16 v[4:7], v[160:163], v[204:207], 0
	v_mfma_f32_16x16x32_bf16 v[0:3], v[168:171], v[204:207], 0
	v_mfma_f32_16x16x32_bf16 v[52:55], v[164:167], v[184:187], v[52:55]
	v_mfma_f32_16x16x32_bf16 v[48:51], v[176:179], v[184:187], v[48:51]
	v_mfma_f32_16x16x32_bf16 v[36:39], v[164:167], v[192:195], v[36:39]
	v_mfma_f32_16x16x32_bf16 v[32:35], v[176:179], v[192:195], v[32:35]
	v_mfma_f32_16x16x32_bf16 v[20:23], v[164:167], v[200:203], v[20:23]
	v_mfma_f32_16x16x32_bf16 v[16:19], v[176:179], v[200:203], v[16:19]
	v_mfma_f32_16x16x32_bf16 v[4:7], v[164:167], v[218:221], v[4:7]
	v_mfma_f32_16x16x32_bf16 v[0:3], v[176:179], v[218:221], v[0:3]
	s_setprio 0
	s_barrier
	s_add_i32 s74, 0, 0x18000
	v_add_u32_e32 v151, s74, v147
	s_add_i32 s75, 0, 0x1c000
	ds_read_b128 v[138:141], v151
	ds_read_b128 v[142:145], v151 offset:1024
	ds_read_b128 v[152:155], v151 offset:2048
	ds_read_b128 v[156:159], v151 offset:3072
	v_add_u32_e32 v151, s75, v147
	ds_read_b128 v[160:163], v151
	ds_read_b128 v[164:167], v151 offset:1024
	ds_read_b128 v[168:171], v151 offset:2048
	ds_read_b128 v[176:179], v151 offset:3072
	s_add_u32 s56, s56, 0x40000
	s_addc_u32 s57, s57, 0
	s_mov_b32 m0, s60
	v_lshl_add_u64 v[226:227], s[56:57], 0, v[132:133]
	ds_read_b128 v[180:183], v150 offset:32768
	ds_read_b128 v[184:187], v150 offset:33792
	ds_read_b128 v[188:191], v150 offset:34816
	ds_read_b128 v[192:195], v150 offset:35840
	ds_read_b128 v[196:199], v150 offset:36864
	ds_read_b128 v[200:203], v150 offset:37888
	ds_read_b128 v[204:207], v150 offset:38912
	ds_read_b128 v[218:221], v150 offset:39936
	global_load_lds_dwordx4 v[226:227], off
	v_lshl_add_u64 v[226:227], s[56:57], 0, v[130:131]
	s_mov_b32 m0, s61
	s_nop 0
	global_load_lds_dwordx4 v[226:227], off
	s_waitcnt vmcnt(8)
	s_waitcnt lgkmcnt(0)
	s_barrier
	s_setprio 1
	s_waitcnt lgkmcnt(0)
	v_mfma_f32_16x16x32_bf16 v[124:127], v[138:141], v[180:183], v[124:127]
	v_mfma_f32_16x16x32_bf16 v[120:123], v[152:155], v[180:183], v[120:123]
	v_mfma_f32_16x16x32_bf16 v[108:111], v[138:141], v[188:191], v[108:111]
	v_mfma_f32_16x16x32_bf16 v[104:107], v[152:155], v[188:191], v[104:107]
	v_mfma_f32_16x16x32_bf16 v[92:95], v[138:141], v[196:199], v[92:95]
	v_mfma_f32_16x16x32_bf16 v[88:91], v[152:155], v[196:199], v[88:91]
	v_mfma_f32_16x16x32_bf16 v[76:79], v[138:141], v[204:207], v[76:79]
	v_mfma_f32_16x16x32_bf16 v[72:75], v[152:155], v[204:207], v[72:75]
	v_mfma_f32_16x16x32_bf16 v[124:127], v[142:145], v[184:187], v[124:127]
	v_mfma_f32_16x16x32_bf16 v[120:123], v[156:159], v[184:187], v[120:123]
	v_mfma_f32_16x16x32_bf16 v[108:111], v[142:145], v[192:195], v[108:111]
	v_mfma_f32_16x16x32_bf16 v[104:107], v[156:159], v[192:195], v[104:107]
	v_mfma_f32_16x16x32_bf16 v[92:95], v[142:145], v[200:203], v[92:95]
	v_mfma_f32_16x16x32_bf16 v[88:91], v[156:159], v[200:203], v[88:91]
	v_mfma_f32_16x16x32_bf16 v[76:79], v[142:145], v[218:221], v[76:79]
	v_mfma_f32_16x16x32_bf16 v[72:75], v[156:159], v[218:221], v[72:75]
	v_mfma_f32_16x16x32_bf16 v[116:119], v[160:163], v[180:183], v[116:119]
	v_mfma_f32_16x16x32_bf16 v[112:115], v[168:171], v[180:183], v[112:115]
	v_mfma_f32_16x16x32_bf16 v[100:103], v[160:163], v[188:191], v[100:103]
	v_mfma_f32_16x16x32_bf16 v[96:99], v[168:171], v[188:191], v[96:99]
	v_mfma_f32_16x16x32_bf16 v[84:87], v[160:163], v[196:199], v[84:87]
	v_mfma_f32_16x16x32_bf16 v[80:83], v[168:171], v[196:199], v[80:83]
	v_mfma_f32_16x16x32_bf16 v[68:71], v[160:163], v[204:207], v[68:71]
	v_mfma_f32_16x16x32_bf16 v[64:67], v[168:171], v[204:207], v[64:67]
	v_mfma_f32_16x16x32_bf16 v[116:119], v[164:167], v[184:187], v[116:119]
	v_mfma_f32_16x16x32_bf16 v[112:115], v[176:179], v[184:187], v[112:115]
	v_mfma_f32_16x16x32_bf16 v[100:103], v[164:167], v[192:195], v[100:103]
	v_mfma_f32_16x16x32_bf16 v[96:99], v[176:179], v[192:195], v[96:99]
	v_mfma_f32_16x16x32_bf16 v[84:87], v[164:167], v[200:203], v[84:87]
	v_mfma_f32_16x16x32_bf16 v[80:83], v[176:179], v[200:203], v[80:83]
	v_mfma_f32_16x16x32_bf16 v[68:71], v[164:167], v[218:221], v[68:71]
	v_mfma_f32_16x16x32_bf16 v[64:67], v[176:179], v[218:221], v[64:67]
	s_setprio 0
	s_barrier
; #define PG8_STAGE(bufoff, gbase, voff) do { _Pragma("unroll") for (int _i = 0; _i < 2; ++_i) \
;         __builtin_amdgcn_global_load_lds((const unsigned*)((const char*)(gbase) + (voff)[_i]), (PG8_LAS unsigned*)(lds + (bufoff) + ldsw + _i * 8192), 16, 0, 0); } while (0)
; #define PG8_LDA(dst, b, h) do { _Pragma("unroll") for (int m = 0; m < 4; ++m) _Pragma("unroll") for (int k = 0; k < 2; ++k) dst[m][k] = *(const PG8_LAS bf16x8*)(lds + PG8_SA(b, h) + aoff + m * 2048 + k * 1024); } while (0)
; #define PG8_MMA(ai, bj, At, Bt) do { __builtin_amdgcn_s_setprio(1); _Pragma("unroll") for (int m = 0; m < 4; ++m) _Pragma("unroll") for (int n = 0; n < 2; ++n) _Pragma("unroll") for (int k = 0; k < 2; ++k) \
;         acc[ai][bj][m][n] = __builtin_amdgcn_mfma_f32_16x16x32_bf16(Bt[n][k], At[m][k], acc[ai][bj][m][n], 0, 0, 0); __builtin_amdgcn_s_setprio(0); } while (0)
; #define PG8_WAIT_V(n) asm volatile("s_waitcnt vmcnt(" #n ")" ::: "memory")
; #define PG8_WAIT_L(n) asm volatile("s_waitcnt lgkmcnt(" #n ")" ::: "memory")
; #define PG8_BAR __builtin_amdgcn_s_barrier()
; #define PG8_SCHED __builtin_amdgcn_sched_barrier(0)
; template <class Epi, class Sched, bool ALIGN_EPI = false, bool SP2 = false>
; __device__ __forceinline__ void gemm_phase(PG8_LAS unsigned char* lds, const Gemm g, const Sched& S, const Epi& E) {
;     ...
;             PG8_LDA(At, 1, 1); PG8_STAGE(PG8_SB(1, 0), b3, voffB); PG8_STAGE(PG8_SB(1, 1), b3 + hstep, voffB); PG8_STAGE(PG8_SA(1, 0), a3, voffA);
;             PG8_WAIT_V(8); PG8_WAIT_L(0); PG8_BAR; PG8_MMA(1, 0, At, B0); PG8_MMA(1, 1, At, B1); PG8_BAR; PG8_SCHED;
	s_add_i32 s56, s74, s8
	v_lshl_add_u64 v[172:173], v[172:173], 0, s[4:5]
	s_mov_b32 m0, s56
	ds_read_b128 v[180:183], v150 offset:49152
	ds_read_b128 v[184:187], v150 offset:50176
	ds_read_b128 v[188:191], v150 offset:51200
	ds_read_b128 v[192:195], v150 offset:52224
	ds_read_b128 v[196:199], v150 offset:53248
	ds_read_b128 v[200:203], v150 offset:54272
	ds_read_b128 v[204:207], v150 offset:55296
	ds_read_b128 v[218:221], v150 offset:56320
	global_load_lds_dwordx4 v[172:173], off
	s_add_i32 m0, s56, 0x2000
	s_add_u32 s38, s38, 0x40080
	v_lshl_add_u64 v[172:173], v[208:209], 0, s[4:5]
	s_addc_u32 s39, s39, 0
	s_add_i32 s56, s75, s8
	global_load_lds_dwordx4 v[172:173], off
	v_lshl_add_u64 v[172:173], s[38:39], 0, v[174:175]
	s_mov_b32 m0, s56
	s_nop 0
	global_load_lds_dwordx4 v[172:173], off
	v_lshl_add_u64 v[172:173], s[38:39], 0, v[128:129]
	s_add_i32 m0, s56, 0x2000
	s_nop 0
	global_load_lds_dwordx4 v[172:173], off
	v_lshl_add_u64 v[172:173], v[222:223], 0, s[4:5]
	s_mov_b32 m0, s62
	s_nop 0
	global_load_lds_dwordx4 v[172:173], off
	v_lshl_add_u64 v[172:173], v[224:225], 0, s[4:5]
	s_mov_b32 m0, s63
	s_nop 0
	global_load_lds_dwordx4 v[172:173], off
	s_waitcnt vmcnt(8)
	s_waitcnt lgkmcnt(0)
	s_barrier
	s_setprio 1
	s_waitcnt lgkmcnt(0)
	v_mfma_f32_16x16x32_bf16 v[60:63], v[138:141], v[180:183], v[60:63]
	v_mfma_f32_16x16x32_bf16 v[56:59], v[152:155], v[180:183], v[56:59]
	v_mfma_f32_16x16x32_bf16 v[44:47], v[138:141], v[188:191], v[44:47]
	v_mfma_f32_16x16x32_bf16 v[40:43], v[152:155], v[188:191], v[40:43]
	v_mfma_f32_16x16x32_bf16 v[28:31], v[138:141], v[196:199], v[28:31]
	v_mfma_f32_16x16x32_bf16 v[24:27], v[152:155], v[196:199], v[24:27]
	v_mfma_f32_16x16x32_bf16 v[12:15], v[138:141], v[204:207], v[12:15]
	v_mfma_f32_16x16x32_bf16 v[8:11], v[152:155], v[204:207], v[8:11]
	v_mfma_f32_16x16x32_bf16 v[60:63], v[142:145], v[184:187], v[60:63]
	v_mfma_f32_16x16x32_bf16 v[56:59], v[156:159], v[184:187], v[56:59]
	v_mfma_f32_16x16x32_bf16 v[44:47], v[142:145], v[192:195], v[44:47]
	v_mfma_f32_16x16x32_bf16 v[40:43], v[156:159], v[192:195], v[40:43]
	v_mfma_f32_16x16x32_bf16 v[28:31], v[142:145], v[200:203], v[28:31]
	v_mfma_f32_16x16x32_bf16 v[24:27], v[156:159], v[200:203], v[24:27]
	v_mfma_f32_16x16x32_bf16 v[12:15], v[142:145], v[218:221], v[12:15]
	v_mfma_f32_16x16x32_bf16 v[8:11], v[156:159], v[218:221], v[8:11]
	v_mfma_f32_16x16x32_bf16 v[52:55], v[160:163], v[180:183], v[52:55]
	v_mfma_f32_16x16x32_bf16 v[48:51], v[168:171], v[180:183], v[48:51]
	v_mfma_f32_16x16x32_bf16 v[36:39], v[160:163], v[188:191], v[36:39]
	v_mfma_f32_16x16x32_bf16 v[32:35], v[168:171], v[188:191], v[32:35]
	v_mfma_f32_16x16x32_bf16 v[20:23], v[160:163], v[196:199], v[20:23]
	v_mfma_f32_16x16x32_bf16 v[16:19], v[168:171], v[196:199], v[16:19]
	v_mfma_f32_16x16x32_bf16 v[4:7], v[160:163], v[204:207], v[4:7]
	v_mfma_f32_16x16x32_bf16 v[0:3], v[168:171], v[204:207], v[0:3]
	v_mfma_f32_16x16x32_bf16 v[52:55], v[164:167], v[184:187], v[52:55]
	v_mfma_f32_16x16x32_bf16 v[48:51], v[176:179], v[184:187], v[48:51]
	v_mfma_f32_16x16x32_bf16 v[36:39], v[164:167], v[192:195], v[36:39]
	v_mfma_f32_16x16x32_bf16 v[32:35], v[176:179], v[192:195], v[32:35]
	v_mfma_f32_16x16x32_bf16 v[20:23], v[164:167], v[200:203], v[20:23]
	v_mfma_f32_16x16x32_bf16 v[16:19], v[176:179], v[200:203], v[16:19]
	v_mfma_f32_16x16x32_bf16 v[4:7], v[164:167], v[218:221], v[4:7]
	v_mfma_f32_16x16x32_bf16 v[0:3], v[176:179], v[218:221], v[0:3]
	s_setprio 0
	s_barrier
	s_add_i32 s73, s73, 2
	s_add_u32 s0, s0, 0x100
	s_addc_u32 s1, s1, 0
	s_add_u32 s71, s71, 0x100
	s_addc_u32 s72, s72, 0
	s_cmp_gt_u32 s73, 13
	s_cbranch_scc0 .LBB0_1752

; #define PG8_STAGE(bufoff, gbase, voff) do { _Pragma("unroll") for (int _i = 0; _i < 2; ++_i) \
;         __builtin_amdgcn_global_load_lds((const unsigned*)((const char*)(gbase) + (voff)[_i]), (PG8_LAS unsigned*)(lds + (bufoff) + ldsw + _i * 8192), 16, 0, 0); } while (0)
; #define PG8_LDA(dst, b, h) do { _Pragma("unroll") for (int m = 0; m < 4; ++m) _Pragma("unroll") for (int k = 0; k < 2; ++k) dst[m][k] = *(const PG8_LAS bf16x8*)(lds + PG8_SA(b, h) + aoff + m * 2048 + k * 1024); } while (0)
; #define PG8_LDB(dst, b, h) do { _Pragma("unroll") for (int n = 0; n < 2; ++n) _Pragma("unroll") for (int k = 0; k < 2; ++k) dst[n][k] = *(const PG8_LAS bf16x8*)(lds + PG8_SB(b, h) + boff + n * 2048 + k * 1024); } while (0)
; #define PG8_MMA(ai, bj, At, Bt) do { __builtin_amdgcn_s_setprio(1); _Pragma("unroll") for (int m = 0; m < 4; ++m) _Pragma("unroll") for (int n = 0; n < 2; ++n) _Pragma("unroll") for (int k = 0; k < 2; ++k) \
;         acc[ai][bj][m][n] = __builtin_amdgcn_mfma_f32_16x16x32_bf16(Bt[n][k], At[m][k], acc[ai][bj][m][n], 0, 0, 0); __builtin_amdgcn_s_setprio(0); } while (0)
; #define PG8_WAIT_V(n) asm volatile("s_waitcnt vmcnt(" #n ")" ::: "memory")
; #define PG8_WAIT_L(n) asm volatile("s_waitcnt lgkmcnt(" #n ")" ::: "memory")
; #define PG8_BAR __builtin_amdgcn_s_barrier()
; #define PG8_SCHED __builtin_amdgcn_sched_barrier(0)
; template <class Epi, class Sched, bool ALIGN_EPI = false, bool SP2 = false>
; __device__ __forceinline__ void gemm_phase(PG8_LAS unsigned char* lds, const Gemm g, const Sched& S, const Epi& E) {
;     ...
;             PG8_LDB(B0, 0, 0); PG8_LDB(B1, 0, 1); PG8_SCHED; PG8_LDA(At, 0, 0); PG8_STAGE(PG8_SA(1, 1), a1 + hstep, voffA);
;             PG8_WAIT_V(8); PG8_WAIT_L(0); PG8_BAR; PG8_MMA(0, 0, At, B0); PG8_MMA(0, 1, At, B1); PG8_BAR; PG8_SCHED;
;             PG8_LDA(At, 0, 1); PG8_STAGE(PG8_SB(0, 0), b2, voffB); PG8_STAGE(PG8_SB(0, 1), b2 + hstep, voffB); PG8_STAGE(PG8_SA(0, 0), a2, voffA);
;             PG8_WAIT_V(8); PG8_WAIT_L(0); PG8_BAR; PG8_MMA(1, 0, At, B0); PG8_MMA(1, 1, At, B1); PG8_BAR; PG8_SCHED;
;     ...
;         for (int a = 0; a < 2; ++a)
; #pragma unroll
;             for (int b = 0; b < 2; ++b)
; #pragma unroll
;                 for (int m = 0; m < 4; ++m)
; #pragma unroll
;                     for (int n = 0; n < 2; ++n) acc[a][b][m][n] = (f32x4){0.f, 0.f, 0.f, 0.f};
.LBB0_1844:
	s_ashr_i32 s49, s48, 31
	s_lshl_b64 s[50:51], s[48:49], 21
	s_add_u32 s50, s14, s50
	s_addc_u32 s51, s15, s51
	s_and_b64 s[52:53], s[42:43], exec
	s_cselect_b32 s49, s51, s1
	s_cselect_b32 s69, s50, s0
	s_ashr_i32 s47, s46, 31
	s_lshl_b64 s[52:53], s[46:47], 21
	s_add_u32 s52, s8, s52
	s_addc_u32 s53, s9, s53
	s_and_b64 s[56:57], s[42:43], exec
	s_cselect_b32 s47, s53, s55
	s_cselect_b32 s70, s52, s54
	s_add_u32 s0, s0, 0x100080
	s_addc_u32 s1, s1, 0
	s_add_u32 s71, s54, 0x100
	s_addc_u32 s72, s55, 0
	s_mov_b32 s73, -2
	s_add_u32 s54, s0, 0xfff00080
	s_addc_u32 s55, s1, -1
	s_add_i32 s74, 0, 0x10000
	s_cmp_eq_u32 s73, 60
	s_cselect_b32 s57, s49, s55
	s_cselect_b32 s56, s69, s54
	s_cselect_b32 s55, s47, s72
	s_cselect_b32 s54, s70, s71
	s_add_i32 s76, 0, 0x14000
	v_add_u32_e32 v140, s74, v189
	v_add_u32_e32 v166, s76, v189
	ds_read_b128 v[128:131], v140
	ds_read_b128 v[132:135], v140 offset:1024
	ds_read_b128 v[136:139], v140 offset:2048
	ds_read_b128 v[140:143], v140 offset:3072
	ds_read_b128 v[144:147], v166
	ds_read_b128 v[148:151], v166 offset:1024
	ds_read_b128 v[162:165], v166 offset:2048
	ds_read_b128 v[166:169], v166 offset:3072
	v_lshl_add_u64 v[208:209], s[0:1], 0, v[158:159]
	s_add_i32 m0, s59, 0xc000
	ds_read_b128 v[170:173], v191
	ds_read_b128 v[176:179], v191 offset:1024
	ds_read_b128 v[180:183], v191 offset:2048
	ds_read_b128 v[184:187], v191 offset:3072
	ds_read_b128 v[192:195], v191 offset:4096
	ds_read_b128 v[196:199], v191 offset:5120
	ds_read_b128 v[200:203], v191 offset:6144
	ds_read_b128 v[204:207], v191 offset:7168
	global_load_lds_dwordx4 v[208:209], off
	v_lshl_add_u64 v[208:209], s[0:1], 0, v[160:161]
	s_add_i32 m0, s59, 0xe000
	s_nop 0
	global_load_lds_dwordx4 v[208:209], off
	s_waitcnt vmcnt(8)
	s_waitcnt lgkmcnt(0)
	s_barrier
	s_setprio 1
	s_waitcnt lgkmcnt(0)
	v_mfma_f32_16x16x32_bf16 v[124:127], v[128:131], v[170:173], 0
	v_mfma_f32_16x16x32_bf16 v[120:123], v[136:139], v[170:173], 0
	v_mfma_f32_16x16x32_bf16 v[108:111], v[128:131], v[180:183], 0
	v_mfma_f32_16x16x32_bf16 v[104:107], v[136:139], v[180:183], 0
	v_mfma_f32_16x16x32_bf16 v[92:95], v[128:131], v[192:195], 0
	v_mfma_f32_16x16x32_bf16 v[88:91], v[136:139], v[192:195], 0
	v_mfma_f32_16x16x32_bf16 v[76:79], v[128:131], v[200:203], 0
	v_mfma_f32_16x16x32_bf16 v[72:75], v[136:139], v[200:203], 0
	v_mfma_f32_16x16x32_bf16 v[124:127], v[132:135], v[176:179], v[124:127]
	v_mfma_f32_16x16x32_bf16 v[120:123], v[140:143], v[176:179], v[120:123]
	v_mfma_f32_16x16x32_bf16 v[108:111], v[132:135], v[184:187], v[108:111]
	v_mfma_f32_16x16x32_bf16 v[104:107], v[140:143], v[184:187], v[104:107]
	v_mfma_f32_16x16x32_bf16 v[92:95], v[132:135], v[196:199], v[92:95]
	v_mfma_f32_16x16x32_bf16 v[88:91], v[140:143], v[196:199], v[88:91]
	v_mfma_f32_16x16x32_bf16 v[76:79], v[132:135], v[204:207], v[76:79]
	v_mfma_f32_16x16x32_bf16 v[72:75], v[140:143], v[204:207], v[72:75]
	v_mfma_f32_16x16x32_bf16 v[116:119], v[144:147], v[170:173], 0
	v_mfma_f32_16x16x32_bf16 v[112:115], v[162:165], v[170:173], 0
	v_mfma_f32_16x16x32_bf16 v[100:103], v[144:147], v[180:183], 0
	v_mfma_f32_16x16x32_bf16 v[96:99], v[162:165], v[180:183], 0
	v_mfma_f32_16x16x32_bf16 v[84:87], v[144:147], v[192:195], 0
	v_mfma_f32_16x16x32_bf16 v[80:83], v[162:165], v[192:195], 0
	v_mfma_f32_16x16x32_bf16 v[68:71], v[144:147], v[200:203], 0
	v_mfma_f32_16x16x32_bf16 v[64:67], v[162:165], v[200:203], 0
	v_mfma_f32_16x16x32_bf16 v[116:119], v[148:151], v[176:179], v[116:119]
	v_mfma_f32_16x16x32_bf16 v[112:115], v[166:169], v[176:179], v[112:115]
	v_mfma_f32_16x16x32_bf16 v[100:103], v[148:151], v[184:187], v[100:103]
	v_mfma_f32_16x16x32_bf16 v[96:99], v[166:169], v[184:187], v[96:99]
	v_mfma_f32_16x16x32_bf16 v[84:87], v[148:151], v[196:199], v[84:87]
	v_mfma_f32_16x16x32_bf16 v[80:83], v[166:169], v[196:199], v[80:83]
	v_mfma_f32_16x16x32_bf16 v[68:71], v[148:151], v[204:207], v[68:71]
	v_mfma_f32_16x16x32_bf16 v[64:67], v[166:169], v[204:207], v[64:67]
	s_setprio 0
	s_barrier
	s_add_i32 s74, s74, s58
	v_lshl_add_u64 v[208:209], s[54:55], 0, v[174:175]
	s_mov_b32 m0, s74
	ds_read_b128 v[170:173], v191 offset:16384
	ds_read_b128 v[176:179], v191 offset:17408
	ds_read_b128 v[180:183], v191 offset:18432
	ds_read_b128 v[184:187], v191 offset:19456
	ds_read_b128 v[192:195], v191 offset:20480
	ds_read_b128 v[196:199], v191 offset:21504
	ds_read_b128 v[200:203], v191 offset:22528
	ds_read_b128 v[204:207], v191 offset:23552
	global_load_lds_dwordx4 v[208:209], off
	s_add_i32 m0, s74, 0x2000
	s_add_u32 s74, s54, 0x100000
	v_lshl_add_u64 v[218:219], s[54:55], 0, v[152:153]
	s_addc_u32 s75, s55, 0
	s_add_i32 s76, s76, s58
	global_load_lds_dwordx4 v[218:219], off
	v_lshl_add_u64 v[220:221], s[74:75], 0, v[174:175]
	s_mov_b32 m0, s76
	v_lshl_add_u64 v[222:223], s[56:57], 0, v[154:155]
	global_load_lds_dwordx4 v[220:221], off
	v_lshl_add_u64 v[220:221], s[74:75], 0, v[152:153]
	s_add_i32 m0, s76, 0x2000
	s_nop 0
	global_load_lds_dwordx4 v[220:221], off
	v_lshl_add_u64 v[220:221], s[56:57], 0, v[156:157]
	s_mov_b32 m0, s59
	s_nop 0
	global_load_lds_dwordx4 v[220:221], off
	s_mov_b32 m0, s60
	s_nop 0
	global_load_lds_dwordx4 v[222:223], off
	s_waitcnt vmcnt(8)
	s_waitcnt lgkmcnt(0)
	s_barrier
; #define PG8_STAGE(bufoff, gbase, voff) do { _Pragma("unroll") for (int _i = 0; _i < 2; ++_i) \
;         __builtin_amdgcn_global_load_lds((const unsigned*)((const char*)(gbase) + (voff)[_i]), (PG8_LAS unsigned*)(lds + (bufoff) + ldsw + _i * 8192), 16, 0, 0); } while (0)
; #define PG8_LDA(dst, b, h) do { _Pragma("unroll") for (int m = 0; m < 4; ++m) _Pragma("unroll") for (int k = 0; k < 2; ++k) dst[m][k] = *(const PG8_LAS bf16x8*)(lds + PG8_SA(b, h) + aoff + m * 2048 + k * 1024); } while (0)
; #define PG8_LDB(dst, b, h) do { _Pragma("unroll") for (int n = 0; n < 2; ++n) _Pragma("unroll") for (int k = 0; k < 2; ++k) dst[n][k] = *(const PG8_LAS bf16x8*)(lds + PG8_SB(b, h) + boff + n * 2048 + k * 1024); } while (0)
; #define PG8_MMA(ai, bj, At, Bt) do { __builtin_amdgcn_s_setprio(1); _Pragma("unroll") for (int m = 0; m < 4; ++m) _Pragma("unroll") for (int n = 0; n < 2; ++n) _Pragma("unroll") for (int k = 0; k < 2; ++k) \
;         acc[ai][bj][m][n] = __builtin_amdgcn_mfma_f32_16x16x32_bf16(Bt[n][k], At[m][k], acc[ai][bj][m][n], 0, 0, 0); __builtin_amdgcn_s_setprio(0); } while (0)
; #define PG8_WAIT_V(n) asm volatile("s_waitcnt vmcnt(" #n ")" ::: "memory")
; #define PG8_WAIT_L(n) asm volatile("s_waitcnt lgkmcnt(" #n ")" ::: "memory")
; #define PG8_BAR __builtin_amdgcn_s_barrier()
; #define PG8_SCHED __builtin_amdgcn_sched_barrier(0)
; template <class Epi, class Sched, bool ALIGN_EPI = false, bool SP2 = false>
; __device__ __forceinline__ void gemm_phase(PG8_LAS unsigned char* lds, const Gemm g, const Sched& S, const Epi& E) {
;     ...
;             PG8_WAIT_V(8); PG8_WAIT_L(0); PG8_BAR; PG8_MMA(1, 0, At, B0); PG8_MMA(1, 1, At, B1); PG8_BAR; PG8_SCHED;
;             PG8_LDB(B0, 1, 0); PG8_LDB(B1, 1, 1); PG8_SCHED; PG8_LDA(At, 1, 0); PG8_STAGE(PG8_SA(0, 1), a2 + hstep, voffA);
;             PG8_WAIT_V(8); PG8_WAIT_L(0); PG8_BAR; PG8_MMA(0, 0, At, B0); PG8_MMA(0, 1, At, B1); PG8_BAR; PG8_SCHED;
	s_setprio 1
	s_waitcnt lgkmcnt(0)
	v_mfma_f32_16x16x32_bf16 v[60:63], v[128:131], v[170:173], 0
	v_mfma_f32_16x16x32_bf16 v[56:59], v[136:139], v[170:173], 0
	v_mfma_f32_16x16x32_bf16 v[44:47], v[128:131], v[180:183], 0
	v_mfma_f32_16x16x32_bf16 v[40:43], v[136:139], v[180:183], 0
	v_mfma_f32_16x16x32_bf16 v[28:31], v[128:131], v[192:195], 0
	v_mfma_f32_16x16x32_bf16 v[24:27], v[136:139], v[192:195], 0
	v_mfma_f32_16x16x32_bf16 v[12:15], v[128:131], v[200:203], 0
	v_mfma_f32_16x16x32_bf16 v[8:11], v[136:139], v[200:203], 0
	v_mfma_f32_16x16x32_bf16 v[60:63], v[132:135], v[176:179], v[60:63]
	v_mfma_f32_16x16x32_bf16 v[56:59], v[140:143], v[176:179], v[56:59]
	v_mfma_f32_16x16x32_bf16 v[44:47], v[132:135], v[184:187], v[44:47]
	v_mfma_f32_16x16x32_bf16 v[40:43], v[140:143], v[184:187], v[40:43]
	v_mfma_f32_16x16x32_bf16 v[28:31], v[132:135], v[196:199], v[28:31]
	v_mfma_f32_16x16x32_bf16 v[24:27], v[140:143], v[196:199], v[24:27]
	v_mfma_f32_16x16x32_bf16 v[12:15], v[132:135], v[204:207], v[12:15]
	v_mfma_f32_16x16x32_bf16 v[8:11], v[140:143], v[204:207], v[8:11]
	v_mfma_f32_16x16x32_bf16 v[52:55], v[144:147], v[170:173], 0
	v_mfma_f32_16x16x32_bf16 v[48:51], v[162:165], v[170:173], 0
	v_mfma_f32_16x16x32_bf16 v[36:39], v[144:147], v[180:183], 0
	v_mfma_f32_16x16x32_bf16 v[32:35], v[162:165], v[180:183], 0
	v_mfma_f32_16x16x32_bf16 v[20:23], v[144:147], v[192:195], 0
	v_mfma_f32_16x16x32_bf16 v[16:19], v[162:165], v[192:195], 0
	v_mfma_f32_16x16x32_bf16 v[4:7], v[144:147], v[200:203], 0
	v_mfma_f32_16x16x32_bf16 v[0:3], v[162:165], v[200:203], 0
	v_mfma_f32_16x16x32_bf16 v[52:55], v[148:151], v[176:179], v[52:55]
	v_mfma_f32_16x16x32_bf16 v[48:51], v[166:169], v[176:179], v[48:51]
	v_mfma_f32_16x16x32_bf16 v[36:39], v[148:151], v[184:187], v[36:39]
	v_mfma_f32_16x16x32_bf16 v[32:35], v[166:169], v[184:187], v[32:35]
	v_mfma_f32_16x16x32_bf16 v[20:23], v[148:151], v[196:199], v[20:23]
	v_mfma_f32_16x16x32_bf16 v[16:19], v[166:169], v[196:199], v[16:19]
	v_mfma_f32_16x16x32_bf16 v[4:7], v[148:151], v[204:207], v[4:7]
	v_mfma_f32_16x16x32_bf16 v[0:3], v[166:169], v[204:207], v[0:3]
	s_setprio 0
	s_barrier
	s_add_i32 s74, 0, 0x18000
	s_add_i32 s75, 0, 0x1c000
	v_add_u32_e32 v140, s74, v189
	v_add_u32_e32 v166, s75, v189
	ds_read_b128 v[128:131], v140
	ds_read_b128 v[132:135], v140 offset:1024
	ds_read_b128 v[136:139], v140 offset:2048
	ds_read_b128 v[140:143], v140 offset:3072
	ds_read_b128 v[144:147], v166
	ds_read_b128 v[148:151], v166 offset:1024
	ds_read_b128 v[162:165], v166 offset:2048
	ds_read_b128 v[166:169], v166 offset:3072
	s_add_u32 s56, s56, 0x100000
	s_addc_u32 s57, s57, 0
	s_mov_b32 m0, s61
	v_lshl_add_u64 v[224:225], s[56:57], 0, v[156:157]
	ds_read_b128 v[170:173], v191 offset:32768
	ds_read_b128 v[176:179], v191 offset:33792
	ds_read_b128 v[180:183], v191 offset:34816
	ds_read_b128 v[184:187], v191 offset:35840
	ds_read_b128 v[192:195], v191 offset:36864
	ds_read_b128 v[196:199], v191 offset:37888
	ds_read_b128 v[200:203], v191 offset:38912
	ds_read_b128 v[204:207], v191 offset:39936
	global_load_lds_dwordx4 v[224:225], off
	v_lshl_add_u64 v[224:225], s[56:57], 0, v[154:155]
	s_mov_b32 m0, s62
	s_nop 0
	global_load_lds_dwordx4 v[224:225], off
	s_waitcnt vmcnt(8)
	s_waitcnt lgkmcnt(0)
	s_barrier
	s_setprio 1
	s_waitcnt lgkmcnt(0)
	v_mfma_f32_16x16x32_bf16 v[124:127], v[128:131], v[170:173], v[124:127]
	v_mfma_f32_16x16x32_bf16 v[120:123], v[136:139], v[170:173], v[120:123]
	v_mfma_f32_16x16x32_bf16 v[108:111], v[128:131], v[180:183], v[108:111]
	v_mfma_f32_16x16x32_bf16 v[104:107], v[136:139], v[180:183], v[104:107]
	v_mfma_f32_16x16x32_bf16 v[92:95], v[128:131], v[192:195], v[92:95]
	v_mfma_f32_16x16x32_bf16 v[88:91], v[136:139], v[192:195], v[88:91]
	v_mfma_f32_16x16x32_bf16 v[76:79], v[128:131], v[200:203], v[76:79]
	v_mfma_f32_16x16x32_bf16 v[72:75], v[136:139], v[200:203], v[72:75]
	v_mfma_f32_16x16x32_bf16 v[124:127], v[132:135], v[176:179], v[124:127]
	v_mfma_f32_16x16x32_bf16 v[120:123], v[140:143], v[176:179], v[120:123]
	v_mfma_f32_16x16x32_bf16 v[108:111], v[132:135], v[184:187], v[108:111]
	v_mfma_f32_16x16x32_bf16 v[104:107], v[140:143], v[184:187], v[104:107]
	v_mfma_f32_16x16x32_bf16 v[92:95], v[132:135], v[196:199], v[92:95]
	v_mfma_f32_16x16x32_bf16 v[88:91], v[140:143], v[196:199], v[88:91]
	v_mfma_f32_16x16x32_bf16 v[76:79], v[132:135], v[204:207], v[76:79]
	v_mfma_f32_16x16x32_bf16 v[72:75], v[140:143], v[204:207], v[72:75]
	v_mfma_f32_16x16x32_bf16 v[116:119], v[144:147], v[170:173], v[116:119]
	v_mfma_f32_16x16x32_bf16 v[112:115], v[162:165], v[170:173], v[112:115]
	v_mfma_f32_16x16x32_bf16 v[100:103], v[144:147], v[180:183], v[100:103]
	v_mfma_f32_16x16x32_bf16 v[96:99], v[162:165], v[180:183], v[96:99]
	v_mfma_f32_16x16x32_bf16 v[84:87], v[144:147], v[192:195], v[84:87]
	v_mfma_f32_16x16x32_bf16 v[80:83], v[162:165], v[192:195], v[80:83]
	v_mfma_f32_16x16x32_bf16 v[68:71], v[144:147], v[200:203], v[68:71]
	v_mfma_f32_16x16x32_bf16 v[64:67], v[162:165], v[200:203], v[64:67]
	v_mfma_f32_16x16x32_bf16 v[116:119], v[148:151], v[176:179], v[116:119]
	v_mfma_f32_16x16x32_bf16 v[112:115], v[166:169], v[176:179], v[112:115]
	v_mfma_f32_16x16x32_bf16 v[100:103], v[148:151], v[184:187], v[100:103]
	v_mfma_f32_16x16x32_bf16 v[96:99], v[166:169], v[184:187], v[96:99]
	v_mfma_f32_16x16x32_bf16 v[84:87], v[148:151], v[196:199], v[84:87]
	v_mfma_f32_16x16x32_bf16 v[80:83], v[166:169], v[196:199], v[80:83]
	v_mfma_f32_16x16x32_bf16 v[68:71], v[148:151], v[204:207], v[68:71]
	v_mfma_f32_16x16x32_bf16 v[64:67], v[166:169], v[204:207], v[64:67]
	s_setprio 0
	s_barrier
; #define PG8_STAGE(bufoff, gbase, voff) do { _Pragma("unroll") for (int _i = 0; _i < 2; ++_i) \
;         __builtin_amdgcn_global_load_lds((const unsigned*)((const char*)(gbase) + (voff)[_i]), (PG8_LAS unsigned*)(lds + (bufoff) + ldsw + _i * 8192), 16, 0, 0); } while (0)
; #define PG8_LDA(dst, b, h) do { _Pragma("unroll") for (int m = 0; m < 4; ++m) _Pragma("unroll") for (int k = 0; k < 2; ++k) dst[m][k] = *(const PG8_LAS bf16x8*)(lds + PG8_SA(b, h) + aoff + m * 2048 + k * 1024); } while (0)
; #define PG8_MMA(ai, bj, At, Bt) do { __builtin_amdgcn_s_setprio(1); _Pragma("unroll") for (int m = 0; m < 4; ++m) _Pragma("unroll") for (int n = 0; n < 2; ++n) _Pragma("unroll") for (int k = 0; k < 2; ++k) \
;         acc[ai][bj][m][n] = __builtin_amdgcn_mfma_f32_16x16x32_bf16(Bt[n][k], At[m][k], acc[ai][bj][m][n], 0, 0, 0); __builtin_amdgcn_s_setprio(0); } while (0)
; #define PG8_WAIT_V(n) asm volatile("s_waitcnt vmcnt(" #n ")" ::: "memory")
; #define PG8_WAIT_L(n) asm volatile("s_waitcnt lgkmcnt(" #n ")" ::: "memory")
; #define PG8_BAR __builtin_amdgcn_s_barrier()
; #define PG8_SCHED __builtin_amdgcn_sched_barrier(0)
; template <class Epi, class Sched, bool ALIGN_EPI = false, bool SP2 = false>
; __device__ __forceinline__ void gemm_phase(PG8_LAS unsigned char* lds, const Gemm g, const Sched& S, const Epi& E) {
;     ...
;             PG8_LDA(At, 1, 1); PG8_STAGE(PG8_SB(1, 0), b3, voffB); PG8_STAGE(PG8_SB(1, 1), b3 + hstep, voffB); PG8_STAGE(PG8_SA(1, 0), a3, voffA);
;             PG8_WAIT_V(8); PG8_WAIT_L(0); PG8_BAR; PG8_MMA(1, 0, At, B0); PG8_MMA(1, 1, At, B1); PG8_BAR; PG8_SCHED;
	s_add_i32 s56, s74, s58
	v_lshl_add_u64 v[208:209], v[208:209], 0, s[4:5]
	s_mov_b32 m0, s56
	ds_read_b128 v[170:173], v191 offset:49152
	ds_read_b128 v[176:179], v191 offset:50176
	ds_read_b128 v[180:183], v191 offset:51200
	ds_read_b128 v[184:187], v191 offset:52224
	ds_read_b128 v[192:195], v191 offset:53248
	ds_read_b128 v[196:199], v191 offset:54272
	ds_read_b128 v[200:203], v191 offset:55296
	ds_read_b128 v[204:207], v191 offset:56320
	global_load_lds_dwordx4 v[208:209], off
	s_add_i32 m0, s56, 0x2000
	s_add_u32 s54, s54, 0x100080
	v_lshl_add_u64 v[208:209], v[218:219], 0, s[4:5]
	s_addc_u32 s55, s55, 0
	s_add_i32 s56, s75, s58
	global_load_lds_dwordx4 v[208:209], off
	v_lshl_add_u64 v[208:209], s[54:55], 0, v[174:175]
	s_mov_b32 m0, s56
	s_nop 0
	global_load_lds_dwordx4 v[208:209], off
	v_lshl_add_u64 v[208:209], s[54:55], 0, v[152:153]
	s_add_i32 m0, s56, 0x2000
	s_nop 0
	global_load_lds_dwordx4 v[208:209], off
	v_lshl_add_u64 v[208:209], v[220:221], 0, s[4:5]
	s_mov_b32 m0, s64
	s_nop 0
	global_load_lds_dwordx4 v[208:209], off
	v_lshl_add_u64 v[208:209], v[222:223], 0, s[4:5]
	s_mov_b32 m0, s65
	s_nop 0
	global_load_lds_dwordx4 v[208:209], off
	s_waitcnt vmcnt(8)
	s_waitcnt lgkmcnt(0)
	s_barrier
	s_setprio 1
	s_waitcnt lgkmcnt(0)
	v_mfma_f32_16x16x32_bf16 v[60:63], v[128:131], v[170:173], v[60:63]
	v_mfma_f32_16x16x32_bf16 v[56:59], v[136:139], v[170:173], v[56:59]
	v_mfma_f32_16x16x32_bf16 v[44:47], v[128:131], v[180:183], v[44:47]
	v_mfma_f32_16x16x32_bf16 v[40:43], v[136:139], v[180:183], v[40:43]
	v_mfma_f32_16x16x32_bf16 v[28:31], v[128:131], v[192:195], v[28:31]
	v_mfma_f32_16x16x32_bf16 v[24:27], v[136:139], v[192:195], v[24:27]
	v_mfma_f32_16x16x32_bf16 v[12:15], v[128:131], v[200:203], v[12:15]
	v_mfma_f32_16x16x32_bf16 v[8:11], v[136:139], v[200:203], v[8:11]
	v_mfma_f32_16x16x32_bf16 v[60:63], v[132:135], v[176:179], v[60:63]
	v_mfma_f32_16x16x32_bf16 v[56:59], v[140:143], v[176:179], v[56:59]
	v_mfma_f32_16x16x32_bf16 v[44:47], v[132:135], v[184:187], v[44:47]
	v_mfma_f32_16x16x32_bf16 v[40:43], v[140:143], v[184:187], v[40:43]
	v_mfma_f32_16x16x32_bf16 v[28:31], v[132:135], v[196:199], v[28:31]
	v_mfma_f32_16x16x32_bf16 v[24:27], v[140:143], v[196:199], v[24:27]
	v_mfma_f32_16x16x32_bf16 v[12:15], v[132:135], v[204:207], v[12:15]
	v_mfma_f32_16x16x32_bf16 v[8:11], v[140:143], v[204:207], v[8:11]
	v_mfma_f32_16x16x32_bf16 v[52:55], v[144:147], v[170:173], v[52:55]
	v_mfma_f32_16x16x32_bf16 v[48:51], v[162:165], v[170:173], v[48:51]
	v_mfma_f32_16x16x32_bf16 v[36:39], v[144:147], v[180:183], v[36:39]
	v_mfma_f32_16x16x32_bf16 v[32:35], v[162:165], v[180:183], v[32:35]
	v_mfma_f32_16x16x32_bf16 v[20:23], v[144:147], v[192:195], v[20:23]
	v_mfma_f32_16x16x32_bf16 v[16:19], v[162:165], v[192:195], v[16:19]
	v_mfma_f32_16x16x32_bf16 v[4:7], v[144:147], v[200:203], v[4:7]
	v_mfma_f32_16x16x32_bf16 v[0:3], v[162:165], v[200:203], v[0:3]
	v_mfma_f32_16x16x32_bf16 v[52:55], v[148:151], v[176:179], v[52:55]
	v_mfma_f32_16x16x32_bf16 v[48:51], v[166:169], v[176:179], v[48:51]
	v_mfma_f32_16x16x32_bf16 v[36:39], v[148:151], v[184:187], v[36:39]
	v_mfma_f32_16x16x32_bf16 v[32:35], v[166:169], v[184:187], v[32:35]
	v_mfma_f32_16x16x32_bf16 v[20:23], v[148:151], v[196:199], v[20:23]
	v_mfma_f32_16x16x32_bf16 v[16:19], v[166:169], v[196:199], v[16:19]
	v_mfma_f32_16x16x32_bf16 v[4:7], v[148:151], v[204:207], v[4:7]
	v_mfma_f32_16x16x32_bf16 v[0:3], v[166:169], v[204:207], v[0:3]
	s_setprio 0
	s_barrier
	s_add_i32 s73, s73, 2
	s_add_u32 s0, s0, 0x100
	s_addc_u32 s1, s1, 0
	s_add_u32 s71, s71, 0x100
	s_addc_u32 s72, s72, 0
	s_cmp_gt_u32 s73, 61
	s_cbranch_scc0 .LBB0_1845
